# GEMM epilogues (in-proj, rwkv in-proj, low-rank): IEEE f32 division expansions replaced by v_rcp_f32 + mul (f32, 1 ulp)
# speedup vs baseline: 1.0039x; 1.0039x over previous
.LBB0_132:
	s_waitcnt lgkmcnt(0)
	ds_read_b128 v[0:3], v22
	v_add_u32_e32 v14, s3, v21
	s_and_saveexec_b64 s[8:9], s[4:5]
	s_xor_b64 s[14:15], exec, s[8:9]
	s_cbranch_execz .LBB0_163
	s_mov_b64 s[34:35], -1
	s_and_b64 vcc, exec, s[18:19]
	s_cbranch_vccz .LBB0_161
	s_and_b64 vcc, exec, s[22:23]
	s_cbranch_vccz .LBB0_158
	s_and_b64 vcc, exec, s[24:25]
	s_cbranch_vccz .LBB0_155
	s_and_b64 vcc, exec, s[26:27]
	s_cbranch_vccz .LBB0_152
	s_and_b64 vcc, exec, s[28:29]
	s_cbranch_vccz .LBB0_149
	s_and_b64 vcc, exec, s[30:31]
	s_cbranch_vccz .LBB0_146
	s_and_saveexec_b64 s[8:9], s[10:11]
	s_xor_b64 s[34:35], exec, s[8:9]
	s_cbranch_execz .LBB0_143
	s_and_saveexec_b64 s[36:37], s[12:13]
	s_cbranch_execz .LBB0_142
	v_ashrrev_i32_e32 v15, 31, v14
	v_lshlrev_b64 v[16:17], 10, v[14:15]
	s_waitcnt lgkmcnt(0)
	v_mul_f32_e32 v15, 0xbfb8aa3b, v0
	v_exp_f32_e32 v15, v15
	v_lshl_add_u64 v[16:17], v[4:5], 0, v[16:17]
	v_add_f32_e32 v15, 1.0, v15
	s_nop 2
	v_rcp_f32_e32 v26, v15
	s_nop 0
	v_mul_f32_e32 v15, v0, v26
	s_nop 1
	v_mul_f32_e32 v26, 0xbfb8aa3b, v1
	v_exp_f32_e32 v26, v26
	s_nop 0
	v_add_f32_e32 v26, 1.0, v26
	s_nop 2
	v_rcp_f32_e32 v27, v26
	s_nop 0
	v_mul_f32_e32 v26, v1, v27
	s_nop 1
	v_mul_f32_e32 v27, 0xbfb8aa3b, v2
	v_exp_f32_e32 v27, v27
	v_cvt_pk_bf16_f32 v26, v15, v26
	s_nop 0
	v_add_f32_e32 v27, 1.0, v27
	s_nop 2
	v_rcp_f32_e32 v28, v27
	s_nop 0
	v_mul_f32_e32 v27, v2, v28
	s_nop 1
	v_mul_f32_e32 v28, 0xbfb8aa3b, v3
	v_exp_f32_e32 v28, v28
	s_nop 0
	v_add_f32_e32 v28, 1.0, v28
	s_nop 4
	v_add_co_u32_e32 v16, vcc, 0x2447e000, v16
	v_rcp_f32_e32 v29, v28
	s_nop 0
	v_mul_f32_e32 v28, v3, v29
	s_nop 2
	v_addc_co_u32_e32 v17, vcc, 0, v17, vcc
	v_cvt_pk_bf16_f32 v27, v27, v28
	global_store_dwordx2 v[16:17], v[26:27], off offset:2016

.LBB0_155:
	s_andn2_b64 vcc, exec, s[34:35]
	s_cbranch_vccnz .LBB0_157
	v_ashrrev_i32_e32 v15, 31, v14
	v_lshlrev_b64 v[16:17], 10, v[14:15]
	s_waitcnt lgkmcnt(0)
	v_mul_f32_e32 v15, 0xbfb8aa3b, v0
	v_exp_f32_e32 v15, v15
	v_lshl_add_u64 v[16:17], v[4:5], 0, v[16:17]
	v_add_f32_e32 v15, 1.0, v15
	s_nop 2
	v_rcp_f32_e32 v26, v15
	s_nop 0
	v_mul_f32_e32 v15, v0, v26
	s_nop 1
	v_mul_f32_e32 v26, 0xbfb8aa3b, v1
	v_exp_f32_e32 v26, v26
	s_nop 0
	v_add_f32_e32 v26, 1.0, v26
	s_nop 2
	v_rcp_f32_e32 v27, v26
	s_nop 0
	v_mul_f32_e32 v26, v1, v27
	s_nop 1
	v_mul_f32_e32 v27, 0xbfb8aa3b, v2
	v_exp_f32_e32 v27, v27
	v_cvt_pk_bf16_f32 v26, v15, v26
	s_nop 0
	v_add_f32_e32 v27, 1.0, v27
	s_nop 2
	v_rcp_f32_e32 v28, v27
	s_nop 0
	v_mul_f32_e32 v27, v2, v28
	s_nop 1
	v_mul_f32_e32 v28, 0xbfb8aa3b, v3
	v_exp_f32_e32 v28, v28
	s_nop 0
	v_add_f32_e32 v28, 1.0, v28
	s_nop 4
	v_add_co_u32_e32 v16, vcc, 0x182ff000, v16
	v_rcp_f32_e32 v29, v28
	s_nop 0
	v_mul_f32_e32 v28, v3, v29
	s_nop 2
	v_addc_co_u32_e32 v17, vcc, 0, v17, vcc
	v_cvt_pk_bf16_f32 v27, v27, v28
	global_store_dwordx2 v[16:17], v[26:27], off offset:1024

.LBB0_161:
	s_andn2_b64 vcc, exec, s[34:35]
	s_cbranch_vccnz .LBB0_163
	s_waitcnt lgkmcnt(0)
	v_mul_f32_e32 v0, 0xbfb8aa3b, v0
	v_exp_f32_e32 v16, v0
	v_mul_f32_e32 v0, 0xbfb8aa3b, v1
	v_exp_f32_e32 v17, v0
	v_mul_f32_e32 v0, 0xbfb8aa3b, v2
	v_exp_f32_e32 v26, v0
	v_mul_f32_e32 v0, 0xbfb8aa3b, v3
	v_ashrrev_i32_e32 v15, 31, v14
	v_exp_f32_e32 v27, v0
	v_lshlrev_b64 v[0:1], 11, v[14:15]
	v_lshl_add_u64 v[14:15], v[8:9], 0, v[0:1]
	global_load_dwordx4 v[0:3], v[12:13], off
	v_pk_add_f32 v[16:17], v[16:17], 1.0 op_sel_hi:[1,0]
	v_pk_add_f32 v[26:27], v[26:27], 1.0 op_sel_hi:[1,0]
	s_nop 1
	s_waitcnt vmcnt(0)
	v_pk_add_f32 v[28:29], v[0:1], 1.0 op_sel_hi:[1,0] neg_lo:[1,0] neg_hi:[1,0]
	v_rcp_f32_e32 v17, v17
	s_nop 3
	v_rcp_f32_e32 v16, v16
	s_nop 2
	v_pk_fma_f32 v[0:1], v[16:17], v[28:29], v[0:1]
	s_nop 1
	v_pk_add_f32 v[16:17], v[2:3], 1.0 op_sel_hi:[1,0] neg_lo:[1,0] neg_hi:[1,0]
	v_rcp_f32_e32 v27, v27
	s_nop 3
	v_rcp_f32_e32 v26, v26
	s_nop 2
	v_pk_fma_f32 v[2:3], v[26:27], v[16:17], v[2:3]
	global_store_dwordx4 v[14:15], v[0:3], off
.LBB0_163:
	s_andn2_saveexec_b64 s[14:15], s[14:15]
	s_cbranch_execz .LBB0_165
	s_waitcnt lgkmcnt(0)
	v_mul_f32_e32 v16, 0xbfb8aa3b, v0
	v_exp_f32_e32 v16, v16
	v_ashrrev_i32_e32 v15, 31, v14
	v_lshlrev_b64 v[14:15], 10, v[14:15]
	v_lshl_add_u64 v[14:15], v[10:11], 0, v[14:15]
	v_add_f32_e32 v16, 1.0, v16
	s_nop 2
	v_rcp_f32_e32 v17, v16
	s_nop 0
	v_mul_f32_e32 v0, v0, v17
	s_nop 1
	v_mul_f32_e32 v16, 0xbfb8aa3b, v1
	v_exp_f32_e32 v16, v16
	s_nop 0
	v_add_f32_e32 v16, 1.0, v16
	s_nop 2
	v_rcp_f32_e32 v17, v16
	s_nop 0
	v_mul_f32_e32 v1, v1, v17
	s_nop 1
	v_mul_f32_e32 v16, 0xbfb8aa3b, v2
	v_exp_f32_e32 v16, v16
	v_cvt_pk_bf16_f32 v0, v0, v1
	s_nop 0
	v_add_f32_e32 v16, 1.0, v16
	s_nop 2
	v_rcp_f32_e32 v17, v16
	s_nop 0
	v_mul_f32_e32 v2, v2, v17
	s_nop 1
	v_mul_f32_e32 v16, 0xbfb8aa3b, v3
	v_exp_f32_e32 v16, v16
	s_nop 0
	v_add_f32_e32 v16, 1.0, v16
	s_nop 2
	v_rcp_f32_e32 v17, v16
	s_nop 0
	v_mul_f32_e32 v3, v3, v17
	s_nop 1
	v_cvt_pk_bf16_f32 v1, v2, v3
	global_store_dwordx2 v[14:15], v[0:1], off
.LBB0_165:
	s_or_b64 exec, exec, s[14:15]
	s_waitcnt lgkmcnt(0)
	ds_read_b128 v[0:3], v23
	v_cndmask_b32_e64 v15, 0, 1, s[18:19]
	v_add_u32_e32 v14, s3, v20
	v_cmp_ne_u32_e64 s[14:15], 1, v15
	s_and_saveexec_b64 s[8:9], s[4:5]
	s_xor_b64 s[34:35], exec, s[8:9]
	s_cbranch_execz .LBB0_196
	s_and_b64 vcc, exec, s[14:15]
	s_mov_b64 s[36:37], -1
	s_cbranch_vccnz .LBB0_194
	s_andn2_b64 vcc, exec, s[22:23]
	s_cbranch_vccnz .LBB0_191
	s_andn2_b64 vcc, exec, s[24:25]
	s_cbranch_vccnz .LBB0_188
	s_andn2_b64 vcc, exec, s[26:27]
	s_cbranch_vccnz .LBB0_185
	s_andn2_b64 vcc, exec, s[28:29]
	s_cbranch_vccnz .LBB0_182
	s_andn2_b64 vcc, exec, s[30:31]
	s_cbranch_vccnz .LBB0_179
	s_and_saveexec_b64 s[8:9], s[10:11]
	s_xor_b64 s[36:37], exec, s[8:9]
	s_cbranch_execz .LBB0_176
	s_and_saveexec_b64 s[38:39], s[12:13]
	s_cbranch_execz .LBB0_175
	v_ashrrev_i32_e32 v15, 31, v14
	v_lshlrev_b64 v[16:17], 10, v[14:15]
	s_waitcnt lgkmcnt(0)
	v_mul_f32_e32 v15, 0xbfb8aa3b, v0
	v_exp_f32_e32 v15, v15
	v_lshl_add_u64 v[16:17], v[4:5], 0, v[16:17]
	v_add_f32_e32 v15, 1.0, v15
	s_nop 2
	v_rcp_f32_e32 v26, v15
	s_nop 0
	v_mul_f32_e32 v15, v0, v26
	s_nop 1
	v_mul_f32_e32 v26, 0xbfb8aa3b, v1
	v_exp_f32_e32 v26, v26
	s_nop 0
	v_add_f32_e32 v26, 1.0, v26
	s_nop 2
	v_rcp_f32_e32 v27, v26
	s_nop 0
	v_mul_f32_e32 v26, v1, v27
	s_nop 1
	v_mul_f32_e32 v27, 0xbfb8aa3b, v2
	v_exp_f32_e32 v27, v27
	v_cvt_pk_bf16_f32 v26, v15, v26
	s_nop 0
	v_add_f32_e32 v27, 1.0, v27
	s_nop 2
	v_rcp_f32_e32 v28, v27
	s_nop 0
	v_mul_f32_e32 v27, v2, v28
	s_nop 1
	v_mul_f32_e32 v28, 0xbfb8aa3b, v3
	v_exp_f32_e32 v28, v28
	s_nop 0
	v_add_f32_e32 v28, 1.0, v28
	s_nop 4
	v_add_co_u32_e32 v16, vcc, 0x2447e000, v16
	v_rcp_f32_e32 v29, v28
	s_nop 0
	v_mul_f32_e32 v28, v3, v29
	s_nop 2
	v_addc_co_u32_e32 v17, vcc, 0, v17, vcc
	v_cvt_pk_bf16_f32 v27, v27, v28
	global_store_dwordx2 v[16:17], v[26:27], off offset:2016

.LBB0_188:
	s_andn2_b64 vcc, exec, s[36:37]
	s_cbranch_vccnz .LBB0_190
	v_ashrrev_i32_e32 v15, 31, v14
	v_lshlrev_b64 v[16:17], 10, v[14:15]
	s_waitcnt lgkmcnt(0)
	v_mul_f32_e32 v15, 0xbfb8aa3b, v0
	v_exp_f32_e32 v15, v15
	v_lshl_add_u64 v[16:17], v[4:5], 0, v[16:17]
	v_add_f32_e32 v15, 1.0, v15
	s_nop 2
	v_rcp_f32_e32 v26, v15
	s_nop 0
	v_mul_f32_e32 v15, v0, v26
	s_nop 1
	v_mul_f32_e32 v26, 0xbfb8aa3b, v1
	v_exp_f32_e32 v26, v26
	s_nop 0
	v_add_f32_e32 v26, 1.0, v26
	s_nop 2
	v_rcp_f32_e32 v27, v26
	s_nop 0
	v_mul_f32_e32 v26, v1, v27
	s_nop 1
	v_mul_f32_e32 v27, 0xbfb8aa3b, v2
	v_exp_f32_e32 v27, v27
	v_cvt_pk_bf16_f32 v26, v15, v26
	s_nop 0
	v_add_f32_e32 v27, 1.0, v27
	s_nop 2
	v_rcp_f32_e32 v28, v27
	s_nop 0
	v_mul_f32_e32 v27, v2, v28
	s_nop 1
	v_mul_f32_e32 v28, 0xbfb8aa3b, v3
	v_exp_f32_e32 v28, v28
	s_nop 0
	v_add_f32_e32 v28, 1.0, v28
	s_nop 4
	v_add_co_u32_e32 v16, vcc, 0x182ff000, v16
	v_rcp_f32_e32 v29, v28
	s_nop 0
	v_mul_f32_e32 v28, v3, v29
	s_nop 2
	v_addc_co_u32_e32 v17, vcc, 0, v17, vcc
	v_cvt_pk_bf16_f32 v27, v27, v28
	global_store_dwordx2 v[16:17], v[26:27], off offset:1024

.LBB0_194:
	s_andn2_b64 vcc, exec, s[36:37]
	s_cbranch_vccnz .LBB0_196
	s_waitcnt lgkmcnt(0)
	v_mul_f32_e32 v0, 0xbfb8aa3b, v0
	v_exp_f32_e32 v16, v0
	v_mul_f32_e32 v0, 0xbfb8aa3b, v1
	v_exp_f32_e32 v17, v0
	v_mul_f32_e32 v0, 0xbfb8aa3b, v2
	v_exp_f32_e32 v26, v0
	v_mul_f32_e32 v0, 0xbfb8aa3b, v3
	v_ashrrev_i32_e32 v15, 31, v14
	v_exp_f32_e32 v27, v0
	v_lshlrev_b64 v[0:1], 11, v[14:15]
	v_lshl_add_u64 v[14:15], v[8:9], 0, v[0:1]
	global_load_dwordx4 v[0:3], v[12:13], off
	v_pk_add_f32 v[16:17], v[16:17], 1.0 op_sel_hi:[1,0]
	v_pk_add_f32 v[26:27], v[26:27], 1.0 op_sel_hi:[1,0]
	s_nop 1
	s_waitcnt vmcnt(0)
	v_pk_add_f32 v[28:29], v[0:1], 1.0 op_sel_hi:[1,0] neg_lo:[1,0] neg_hi:[1,0]
	v_rcp_f32_e32 v17, v17
	s_nop 3
	v_rcp_f32_e32 v16, v16
	s_nop 2
	v_pk_fma_f32 v[0:1], v[16:17], v[28:29], v[0:1]
	s_nop 1
	v_pk_add_f32 v[16:17], v[2:3], 1.0 op_sel_hi:[1,0] neg_lo:[1,0] neg_hi:[1,0]
	v_rcp_f32_e32 v27, v27
	s_nop 3
	v_rcp_f32_e32 v26, v26
	s_nop 2
	v_pk_fma_f32 v[2:3], v[26:27], v[16:17], v[2:3]
	global_store_dwordx4 v[14:15], v[0:3], off
.LBB0_196:
	s_andn2_saveexec_b64 s[34:35], s[34:35]
	s_cbranch_execz .LBB0_198
	s_waitcnt lgkmcnt(0)
	v_mul_f32_e32 v16, 0xbfb8aa3b, v0
	v_exp_f32_e32 v16, v16
	v_ashrrev_i32_e32 v15, 31, v14
	v_lshlrev_b64 v[14:15], 10, v[14:15]
	v_lshl_add_u64 v[14:15], v[10:11], 0, v[14:15]
	v_add_f32_e32 v16, 1.0, v16
	s_nop 2
	v_rcp_f32_e32 v17, v16
	s_nop 0
	v_mul_f32_e32 v0, v0, v17
	s_nop 1
	v_mul_f32_e32 v16, 0xbfb8aa3b, v1
	v_exp_f32_e32 v16, v16
	s_nop 0
	v_add_f32_e32 v16, 1.0, v16
	s_nop 2
	v_rcp_f32_e32 v17, v16
	s_nop 0
	v_mul_f32_e32 v1, v1, v17
	s_nop 1
	v_mul_f32_e32 v16, 0xbfb8aa3b, v2
	v_exp_f32_e32 v16, v16
	v_cvt_pk_bf16_f32 v0, v0, v1
	s_nop 0
	v_add_f32_e32 v16, 1.0, v16
	s_nop 2
	v_rcp_f32_e32 v17, v16
	s_nop 0
	v_mul_f32_e32 v2, v2, v17
	s_nop 1
	v_mul_f32_e32 v16, 0xbfb8aa3b, v3
	v_exp_f32_e32 v16, v16
	s_nop 0
	v_add_f32_e32 v16, 1.0, v16
	s_nop 2
	v_rcp_f32_e32 v17, v16
	s_nop 0
	v_mul_f32_e32 v3, v3, v17
	s_nop 1
	v_cvt_pk_bf16_f32 v1, v2, v3
	global_store_dwordx2 v[14:15], v[0:1], off
.LBB0_198:
	s_or_b64 exec, exec, s[34:35]
	s_waitcnt lgkmcnt(0)
	ds_read_b128 v[0:3], v24
	v_add_u32_e32 v14, s3, v19
	s_and_saveexec_b64 s[8:9], s[4:5]
	s_xor_b64 s[34:35], exec, s[8:9]
	s_cbranch_execz .LBB0_229
	s_and_b64 vcc, exec, s[14:15]
	s_mov_b64 s[36:37], -1
	s_cbranch_vccnz .LBB0_227
	s_andn2_b64 vcc, exec, s[22:23]
	s_cbranch_vccnz .LBB0_224
	s_andn2_b64 vcc, exec, s[24:25]
	s_cbranch_vccnz .LBB0_221
	s_andn2_b64 vcc, exec, s[26:27]
	s_cbranch_vccnz .LBB0_218
	s_andn2_b64 vcc, exec, s[28:29]
	s_cbranch_vccnz .LBB0_215
	s_andn2_b64 vcc, exec, s[30:31]
	s_cbranch_vccnz .LBB0_212
	s_and_saveexec_b64 s[8:9], s[10:11]
	s_xor_b64 s[36:37], exec, s[8:9]
	s_cbranch_execz .LBB0_209
	s_and_saveexec_b64 s[38:39], s[12:13]
	s_cbranch_execz .LBB0_208
	v_ashrrev_i32_e32 v15, 31, v14
	v_lshlrev_b64 v[16:17], 10, v[14:15]
	s_waitcnt lgkmcnt(0)
	v_mul_f32_e32 v15, 0xbfb8aa3b, v0
	v_exp_f32_e32 v15, v15
	v_lshl_add_u64 v[16:17], v[4:5], 0, v[16:17]
	v_add_f32_e32 v15, 1.0, v15
	s_nop 2
	v_rcp_f32_e32 v26, v15
	s_nop 0
	v_mul_f32_e32 v15, v0, v26
	s_nop 1
	v_mul_f32_e32 v26, 0xbfb8aa3b, v1
	v_exp_f32_e32 v26, v26
	s_nop 0
	v_add_f32_e32 v26, 1.0, v26
	s_nop 2
	v_rcp_f32_e32 v27, v26
	s_nop 0
	v_mul_f32_e32 v26, v1, v27
	s_nop 1
	v_mul_f32_e32 v27, 0xbfb8aa3b, v2
	v_exp_f32_e32 v27, v27
	v_cvt_pk_bf16_f32 v26, v15, v26
	s_nop 0
	v_add_f32_e32 v27, 1.0, v27
	s_nop 2
	v_rcp_f32_e32 v28, v27
	s_nop 0
	v_mul_f32_e32 v27, v2, v28
	s_nop 1
	v_mul_f32_e32 v28, 0xbfb8aa3b, v3
	v_exp_f32_e32 v28, v28
	s_nop 0
	v_add_f32_e32 v28, 1.0, v28
	s_nop 4
	v_add_co_u32_e32 v16, vcc, 0x2447e000, v16
	v_rcp_f32_e32 v29, v28
	s_nop 0
	v_mul_f32_e32 v28, v3, v29
	s_nop 2
	v_addc_co_u32_e32 v17, vcc, 0, v17, vcc
	v_cvt_pk_bf16_f32 v27, v27, v28
	global_store_dwordx2 v[16:17], v[26:27], off offset:2016

.LBB0_231:
	s_or_b64 exec, exec, s[34:35]
	s_waitcnt lgkmcnt(0)
	ds_read_b128 v[0:3], v25
	v_add_u32_e32 v14, s3, v18
	s_and_saveexec_b64 s[8:9], s[4:5]
	s_xor_b64 s[34:35], exec, s[8:9]
	s_cbranch_execz .LBB0_262
	s_and_b64 vcc, exec, s[14:15]
	s_mov_b64 s[14:15], -1
	s_cbranch_vccnz .LBB0_260
	s_andn2_b64 vcc, exec, s[22:23]
	s_cbranch_vccnz .LBB0_257
	s_andn2_b64 vcc, exec, s[24:25]
	s_cbranch_vccnz .LBB0_254
	s_andn2_b64 vcc, exec, s[26:27]
	s_cbranch_vccnz .LBB0_251
	s_andn2_b64 vcc, exec, s[28:29]
	s_cbranch_vccnz .LBB0_248
	s_andn2_b64 vcc, exec, s[30:31]
	s_cbranch_vccnz .LBB0_245
	s_and_saveexec_b64 s[8:9], s[10:11]
	s_xor_b64 s[14:15], exec, s[8:9]
	s_cbranch_execz .LBB0_242
	s_and_saveexec_b64 s[36:37], s[12:13]
	s_cbranch_execz .LBB0_241
	v_ashrrev_i32_e32 v15, 31, v14
	v_lshlrev_b64 v[16:17], 10, v[14:15]
	s_waitcnt lgkmcnt(0)
	v_mul_f32_e32 v15, 0xbfb8aa3b, v0
	v_exp_f32_e32 v15, v15
	v_lshl_add_u64 v[16:17], v[4:5], 0, v[16:17]
	v_add_f32_e32 v15, 1.0, v15
	s_nop 2
	v_rcp_f32_e32 v26, v15
	s_nop 0
	v_mul_f32_e32 v15, v0, v26
	s_nop 1
	v_mul_f32_e32 v26, 0xbfb8aa3b, v1
	v_exp_f32_e32 v26, v26
	s_nop 0
	v_add_f32_e32 v26, 1.0, v26
	s_nop 2
	v_rcp_f32_e32 v27, v26
	s_nop 0
	v_mul_f32_e32 v26, v1, v27
	s_nop 1
	v_mul_f32_e32 v27, 0xbfb8aa3b, v2
	v_exp_f32_e32 v27, v27
	v_cvt_pk_bf16_f32 v26, v15, v26
	s_nop 0
	v_add_f32_e32 v27, 1.0, v27
	s_nop 2
	v_rcp_f32_e32 v28, v27
	s_nop 0
	v_mul_f32_e32 v27, v2, v28
	s_nop 1
	v_mul_f32_e32 v28, 0xbfb8aa3b, v3
	v_exp_f32_e32 v28, v28
	s_nop 0
	v_add_f32_e32 v28, 1.0, v28
	s_nop 4
	v_add_co_u32_e32 v16, vcc, 0x2447e000, v16
	v_rcp_f32_e32 v29, v28
	s_nop 0
	v_mul_f32_e32 v28, v3, v29
	s_nop 2
	v_addc_co_u32_e32 v17, vcc, 0, v17, vcc
	v_cvt_pk_bf16_f32 v27, v27, v28
	global_store_dwordx2 v[16:17], v[26:27], off offset:2016

.LBB0_254:
	s_andn2_b64 vcc, exec, s[14:15]
	s_cbranch_vccnz .LBB0_256
	v_ashrrev_i32_e32 v15, 31, v14
	v_lshlrev_b64 v[16:17], 10, v[14:15]
	s_waitcnt lgkmcnt(0)
	v_mul_f32_e32 v15, 0xbfb8aa3b, v0
	v_exp_f32_e32 v15, v15
	v_lshl_add_u64 v[16:17], v[4:5], 0, v[16:17]
	v_add_f32_e32 v15, 1.0, v15
	s_nop 2
	v_rcp_f32_e32 v26, v15
	s_nop 0
	v_mul_f32_e32 v15, v0, v26
	s_nop 1
	v_mul_f32_e32 v26, 0xbfb8aa3b, v1
	v_exp_f32_e32 v26, v26
	s_nop 0
	v_add_f32_e32 v26, 1.0, v26
	s_nop 2
	v_rcp_f32_e32 v27, v26
	s_nop 0
	v_mul_f32_e32 v26, v1, v27
	s_nop 1
	v_mul_f32_e32 v27, 0xbfb8aa3b, v2
	v_exp_f32_e32 v27, v27
	v_cvt_pk_bf16_f32 v26, v15, v26
	s_nop 0
	v_add_f32_e32 v27, 1.0, v27
	s_nop 2
	v_rcp_f32_e32 v28, v27
	s_nop 0
	v_mul_f32_e32 v27, v2, v28
	s_nop 1
	v_mul_f32_e32 v28, 0xbfb8aa3b, v3
	v_exp_f32_e32 v28, v28
	s_nop 0
	v_add_f32_e32 v28, 1.0, v28
	s_nop 4
	v_add_co_u32_e32 v16, vcc, 0x182ff000, v16
	v_rcp_f32_e32 v29, v28
	s_nop 0
	v_mul_f32_e32 v28, v3, v29
	s_nop 2
	v_addc_co_u32_e32 v17, vcc, 0, v17, vcc
	v_cvt_pk_bf16_f32 v27, v27, v28
	global_store_dwordx2 v[16:17], v[26:27], off offset:1024

.LBB0_260:
	s_andn2_b64 vcc, exec, s[14:15]
	s_cbranch_vccnz .LBB0_262
	s_waitcnt lgkmcnt(0)
	v_mul_f32_e32 v0, 0xbfb8aa3b, v0
	v_exp_f32_e32 v16, v0
	v_mul_f32_e32 v0, 0xbfb8aa3b, v1
	v_exp_f32_e32 v17, v0
	v_mul_f32_e32 v0, 0xbfb8aa3b, v2
	v_exp_f32_e32 v26, v0
	v_mul_f32_e32 v0, 0xbfb8aa3b, v3
	v_ashrrev_i32_e32 v15, 31, v14
	v_exp_f32_e32 v27, v0
	v_lshlrev_b64 v[0:1], 11, v[14:15]
	v_lshl_add_u64 v[14:15], v[8:9], 0, v[0:1]
	global_load_dwordx4 v[0:3], v[12:13], off
	v_pk_add_f32 v[16:17], v[16:17], 1.0 op_sel_hi:[1,0]
	v_pk_add_f32 v[26:27], v[26:27], 1.0 op_sel_hi:[1,0]
	s_nop 1
	s_waitcnt vmcnt(0)
	v_pk_add_f32 v[28:29], v[0:1], 1.0 op_sel_hi:[1,0] neg_lo:[1,0] neg_hi:[1,0]
	v_rcp_f32_e32 v17, v17
	s_nop 3
	v_rcp_f32_e32 v16, v16
	s_nop 2
	v_pk_fma_f32 v[0:1], v[16:17], v[28:29], v[0:1]
	s_nop 1
	v_pk_add_f32 v[16:17], v[2:3], 1.0 op_sel_hi:[1,0] neg_lo:[1,0] neg_hi:[1,0]
	v_rcp_f32_e32 v27, v27
	s_nop 3
	v_rcp_f32_e32 v26, v26
	s_nop 2
	v_pk_fma_f32 v[2:3], v[26:27], v[16:17], v[2:3]
	global_store_dwordx4 v[14:15], v[0:3], off
.LBB0_262:
	s_andn2_saveexec_b64 s[14:15], s[34:35]
	s_cbranch_execz .LBB0_131
	s_waitcnt lgkmcnt(0)
	v_mul_f32_e32 v16, 0xbfb8aa3b, v0
	v_exp_f32_e32 v16, v16
	v_ashrrev_i32_e32 v15, 31, v14
	v_lshlrev_b64 v[14:15], 10, v[14:15]
	v_lshl_add_u64 v[14:15], v[10:11], 0, v[14:15]
	v_add_f32_e32 v16, 1.0, v16
	s_nop 2
	v_rcp_f32_e32 v17, v16
	s_nop 0
	v_mul_f32_e32 v0, v0, v17
	s_nop 1
	v_mul_f32_e32 v16, 0xbfb8aa3b, v1
	v_exp_f32_e32 v16, v16
	s_nop 0
	v_add_f32_e32 v16, 1.0, v16
	s_nop 2
	v_rcp_f32_e32 v17, v16
	s_nop 0
	v_mul_f32_e32 v1, v1, v17
	s_nop 1
	v_mul_f32_e32 v16, 0xbfb8aa3b, v2
	v_exp_f32_e32 v16, v16
	v_cvt_pk_bf16_f32 v0, v0, v1
	s_nop 0
	v_add_f32_e32 v16, 1.0, v16
	s_nop 2
	v_rcp_f32_e32 v17, v16
	s_nop 0
	v_mul_f32_e32 v2, v2, v17
	s_nop 1
	v_mul_f32_e32 v16, 0xbfb8aa3b, v3
	v_exp_f32_e32 v16, v16
	s_nop 0
	v_add_f32_e32 v16, 1.0, v16
	s_nop 2
	v_rcp_f32_e32 v17, v16
	s_nop 0
	v_mul_f32_e32 v3, v3, v17
	s_nop 1
	v_cvt_pk_bf16_f32 v1, v2, v3
	global_store_dwordx2 v[14:15], v[0:1], off
	s_branch .LBB0_131

.LBB0_276:
	s_lshl_b32 s10, s17, 5
	s_lshl_b32 s4, s17, 12
	s_add_i32 s20, s10, 0xfe00
	s_and_b64 s[10:11], s[12:13], exec
	s_cselect_b32 s54, s4, s20
	s_lshl_b32 s4, s19, 6
	s_waitcnt vmcnt(5)
	v_or_b32_e32 v0, s4, v154
	v_readlane_b32 s36, v253, 26
	v_lshlrev_b32_e32 v48, 2, v0
	v_readlane_b32 s38, v253, 28
	v_readlane_b32 s39, v253, 29
	s_and_b64 s[10:11], s[12:13], exec
	v_readlane_b32 s50, v253, 40
	v_lshl_add_u64 v[0:1], s[38:39], 0, v[48:49]
	v_add_co_u32_e32 v2, vcc, 0x1000, v0
	v_readlane_b32 s51, v253, 41
	s_nop 0
	v_addc_co_u32_e32 v3, vcc, 0, v1, vcc
	s_cselect_b32 s10, 0x1000, 32
	v_lshl_add_u32 v187, s18, 6, v150
	s_waitcnt vmcnt(1)
	v_add_co_u32_e32 v4, vcc, 0x2000, v0
	v_cmp_gt_u32_e64 s[50:51], s10, v187
	s_waitcnt vmcnt(0)
	v_addc_co_u32_e32 v5, vcc, 0, v1, vcc
	global_load_dword v66, v[2:3], off offset:2048
	global_load_dword v67, v[2:3], off offset:3072
	global_load_dword v68, v[4:5], off
	global_load_dword v69, v[4:5], off offset:1024
	global_load_dword v64, v[4:5], off offset:2048
	global_load_dword v65, v[4:5], off offset:3072
	v_cndmask_b32_e64 v4, 0, v187, s[50:51]
	v_add_u32_e32 v32, s54, v4
	v_ashrrev_i32_e32 v33, 31, v32
	v_lshlrev_b64 v[4:5], 6, v[32:33]
	v_add_co_u32_e32 v0, vcc, 0x3000, v0
	v_lshl_add_u64 v[34:35], s[6:7], 0, v[4:5]
	v_readlane_b32 s40, v253, 30
	v_readlane_b32 s41, v253, 31
	v_addc_co_u32_e32 v1, vcc, 0, v1, vcc
	global_load_dwordx4 v[8:11], v[34:35], off offset:16
	global_load_dwordx4 v[12:15], v[34:35], off
	global_load_dwordx4 v[36:39], v[34:35], off offset:48
	global_load_dwordx4 v[40:43], v[34:35], off offset:32
	global_load_dword v139, v48, s[38:39]
	global_load_dword v138, v48, s[40:41]
	global_load_dword v72, v[0:1], off
	global_load_dword v73, v[0:1], off offset:1024
	global_load_dword v70, v[0:1], off offset:2048
	global_load_dword v140, v48, s[38:39] offset:1024
	global_load_dword v71, v[0:1], off offset:3072
	global_load_dword v141, v48, s[38:39] offset:2048
	global_load_dword v143, v48, s[38:39] offset:3072
	global_load_dword v142, v[2:3], off
	s_nop 0
	global_load_dword v48, v[2:3], off offset:1024
	v_readlane_b32 s48, v253, 38
	v_readlane_b32 s49, v253, 39
	v_or_b32_e32 v186, 1, v187
	v_readlane_b32 s44, v253, 34
	v_readlane_b32 s45, v253, 35
	v_or_b32_e32 v184, 2, v187
	v_or_b32_e32 v182, 3, v187
	v_cmp_gt_u32_e64 s[48:49], s10, v186
	v_cmp_gt_u32_e64 s[44:45], s10, v184
	v_cmp_gt_u32_e64 s[40:41], s10, v182
	v_cndmask_b32_e64 v0, 0, v186, s[48:49]
	v_cndmask_b32_e64 v1, 0, v184, s[44:45]
	v_cndmask_b32_e64 v2, 0, v182, s[40:41]
	v_add_u32_e32 v136, s54, v0
	v_add_u32_e32 v132, s54, v1
	v_add_u32_e32 v128, s54, v2
	v_ashrrev_i32_e32 v137, 31, v136
	v_ashrrev_i32_e32 v133, 31, v132
	v_ashrrev_i32_e32 v129, 31, v128
	v_lshlrev_b64 v[0:1], 6, v[136:137]
	v_lshlrev_b64 v[2:3], 6, v[132:133]
	v_lshlrev_b64 v[4:5], 6, v[128:129]
	v_lshl_add_u64 v[44:45], s[6:7], 0, v[0:1]
	v_lshl_add_u64 v[134:135], s[6:7], 0, v[2:3]
	v_lshl_add_u64 v[130:131], s[6:7], 0, v[4:5]
	global_load_dwordx4 v[74:77], v[44:45], off offset:16
	global_load_dwordx4 v[78:81], v[44:45], off
	global_load_dwordx4 v[82:85], v[44:45], off offset:48
	global_load_dwordx4 v[86:89], v[44:45], off offset:32
	global_load_dwordx4 v[24:27], v[134:135], off offset:16
	global_load_dwordx4 v[28:31], v[134:135], off
	global_load_dwordx4 v[16:19], v[134:135], off offset:48
	global_load_dwordx4 v[20:23], v[134:135], off offset:32
	global_load_dwordx4 v[0:3], v[130:131], off offset:16
	global_load_dwordx4 v[4:7], v[130:131], off
	s_mov_b32 s11, 0x3d800000
	v_readlane_b32 s37, v253, 27
	v_readlane_b32 s42, v253, 32
	v_readlane_b32 s43, v253, 33
	v_readlane_b32 s46, v253, 36
	v_readlane_b32 s47, v253, 37
	s_waitcnt vmcnt(24)
	v_pk_mul_f32 v[10:11], v[66:67], v[10:11]
	s_waitcnt vmcnt(21)
	v_pk_mul_f32 v[40:41], v[68:69], v[40:41]
	v_pk_mul_f32 v[42:43], v[64:65], v[42:43]
	s_waitcnt vmcnt(19)
	v_fma_f32 v12, v139, v12, v138
	s_waitcnt vmcnt(17)
	v_pk_mul_f32 v[36:37], v[72:73], v[36:37]
	s_waitcnt vmcnt(15)
	v_fmac_f32_e32 v12, v140, v13
	s_waitcnt vmcnt(14)
	v_pk_mul_f32 v[38:39], v[70:71], v[38:39]
	s_waitcnt vmcnt(13)
	v_fmac_f32_e32 v12, v141, v14
	s_waitcnt vmcnt(12)
	v_fmac_f32_e32 v12, v143, v15
	s_waitcnt vmcnt(11)
	v_fmac_f32_e32 v12, v142, v8
	s_waitcnt vmcnt(10)
	v_fmac_f32_e32 v12, v48, v9
	v_add_f32_e32 v8, v12, v10
	v_add_f32_e32 v8, v8, v11
	v_add_f32_e32 v8, v8, v40
	v_add_f32_e32 v8, v8, v41
	v_add_f32_e32 v8, v8, v42
	v_add_f32_e32 v8, v8, v43
	v_add_f32_e32 v8, v8, v36
	v_add_f32_e32 v8, v8, v37
	v_add_f32_e32 v8, v8, v38
	v_add_f32_e32 v36, v8, v39
	v_mul_f32_e64 v8, |v36|, s97
	v_exp_f32_e32 v38, v8
	v_min_f32_e32 v39, 0, v36
	global_load_dwordx4 v[8:11], v[130:131], off offset:48
	global_load_dwordx4 v[12:15], v[130:131], off offset:32
	s_nop 1
	s_waitcnt vmcnt(6)
	v_fma_f32 v28, v139, v28, v138
	v_fmac_f32_e32 v28, v140, v29
	s_nop 1
	v_fmac_f32_e32 v28, v141, v30
	v_fmac_f32_e32 v28, v143, v31
	s_nop 1
	v_fmac_f32_e32 v28, v142, v24
	v_fmac_f32_e32 v28, v48, v25
	s_nop 1
	v_pk_mul_f32 v[24:25], v[66:67], v[26:27]
	s_waitcnt vmcnt(4)
	v_pk_mul_f32 v[20:21], v[68:69], v[20:21]
	s_nop 1
	v_add_f32_e32 v24, v28, v24
	v_add_f32_e32 v24, v24, v25
	v_add_f32_e32 v36, 1.0, v38
	v_log_f32_e32 v36, v36
	s_nop 0
	v_mul_f32_e32 v36, 0x3f317218, v36
	s_nop 1
	v_sub_f32_e32 v38, v39, v36
	v_fma_f32 v39, v139, v78, v138
	v_fmac_f32_e32 v39, v140, v79
	v_fmac_f32_e32 v39, v141, v80
	v_fmac_f32_e32 v39, v143, v81
	v_fmac_f32_e32 v39, v142, v74
	v_fmac_f32_e32 v39, v48, v75
	v_pk_mul_f32 v[36:37], v[66:67], v[76:77]
	v_add_f32_e32 v20, v24, v20
	v_add_f32_e32 v36, v39, v36
	v_add_f32_e32 v39, v36, v37
	v_pk_mul_f32 v[36:37], v[68:69], v[86:87]
	v_add_f32_e32 v24, v20, v21
	v_add_f32_e32 v36, v39, v36
	v_add_f32_e32 v39, v36, v37
	v_pk_mul_f32 v[36:37], v[64:65], v[88:89]
	v_pk_mul_f32 v[20:21], v[64:65], v[22:23]
	v_add_f32_e32 v36, v39, v36
	v_add_f32_e32 v39, v36, v37
	v_pk_mul_f32 v[36:37], v[72:73], v[82:83]
	v_add_f32_e32 v20, v24, v20
	v_add_f32_e32 v36, v39, v36
	v_add_f32_e32 v39, v36, v37
	v_pk_mul_f32 v[36:37], v[70:71], v[84:85]
	v_add_f32_e32 v20, v20, v21
	v_add_f32_e32 v36, v39, v36
	v_add_f32_e32 v36, v36, v37
	v_mul_f32_e64 v37, |v36|, s97
	v_exp_f32_e32 v39, v37
	v_fma_f32 v37, v38, s11, 0
	v_min_f32_e32 v40, 0, v36
	v_cndmask_b32_e64 v38, 0, v37, s[50:51]
	s_nop 1
	v_pk_mul_f32 v[16:17], v[72:73], v[16:17]
	s_waitcnt vmcnt(2)
	v_fma_f32 v4, v139, v4, v138
	s_nop 1
	v_add_f32_e32 v16, v20, v16
	s_nop 1
	v_add_f32_e32 v20, v16, v17
	v_pk_mul_f32 v[16:17], v[70:71], v[18:19]
	s_nop 1
	v_add_f32_e32 v16, v20, v16
	s_nop 1
	v_add_f32_e32 v16, v16, v17
	v_mul_f32_e64 v17, |v16|, s97
	s_nop 1
	v_exp_f32_e32 v18, v17
	v_min_f32_e32 v20, 0, v16
	s_nop 1
	v_fmac_f32_e32 v4, v140, v5
	v_add_f32_e32 v36, 1.0, v39
	v_log_f32_e32 v36, v36
	s_nop 0
	v_mul_f32_e32 v36, 0x3f317218, v36
	s_nop 1
	v_sub_f32_e32 v36, v40, v36
	v_mul_f32_e32 v36, 0x3d800000, v36
	v_cndmask_b32_e64 v17, 0, v36, s[48:49]
	v_add_f32_e32 v19, v38, v17
	s_nop 1
	v_fmac_f32_e32 v4, v141, v6
	v_fmac_f32_e32 v4, v143, v7
	s_nop 1
	v_fmac_f32_e32 v4, v142, v0
	s_nop 1
	v_fmac_f32_e32 v4, v48, v1
	v_pk_mul_f32 v[0:1], v[66:67], v[2:3]
	s_nop 1
	v_add_f32_e32 v0, v4, v0
	v_add_f32_e32 v2, v0, v1
	s_nop 1
	s_waitcnt vmcnt(0)
	v_pk_mul_f32 v[0:1], v[68:69], v[12:13]
	s_nop 1
	v_add_f32_e32 v0, v2, v0
	v_add_f32_e32 v2, v0, v1
	s_nop 1
	v_pk_mul_f32 v[0:1], v[64:65], v[14:15]
	s_nop 0
	v_add_f32_e32 v16, 1.0, v18
	v_log_f32_e32 v16, v16
	s_nop 0
	v_mul_f32_e32 v16, 0x3f317218, v16
	s_nop 1
	v_add_f32_e32 v0, v2, v0
	v_sub_f32_e32 v16, v20, v16
	v_add_f32_e32 v2, v0, v1
	v_pk_mul_f32 v[0:1], v[72:73], v[8:9]
	v_mul_f32_e32 v16, 0x3d800000, v16
	v_add_f32_e32 v0, v2, v0
	v_cndmask_b32_e64 v16, 0, v16, s[44:45]
	v_add_f32_e32 v2, v0, v1
	v_add_f32_e32 v16, v19, v16
	v_pk_mul_f32 v[0:1], v[70:71], v[10:11]
	v_or_b32_e32 v185, 4, v187
	v_add_f32_e32 v0, v2, v0
	v_add_f32_e32 v0, v0, v1
	v_mul_f32_e64 v1, |v0|, s97
	v_exp_f32_e32 v2, v1
	v_min_f32_e32 v3, 0, v0
	v_cmp_gt_u32_e64 s[46:47], s10, v185
	v_or_b32_e32 v183, 5, v187
	s_nop 1
	v_cmp_gt_u32_e64 s[42:43], s10, v183
	v_or_b32_e32 v180, 6, v187
	s_nop 1
	v_cndmask_b32_e64 v0, 0, v185, s[46:47]
	s_nop 1
	v_add_u32_e32 v110, s54, v0
	s_nop 1
	v_ashrrev_i32_e32 v111, 31, v110
	s_nop 1
	v_lshlrev_b64 v[0:1], 6, v[110:111]
	v_lshl_add_u64 v[112:113], s[6:7], 0, v[0:1]
	global_load_dwordx4 v[8:11], v[112:113], off offset:16
	global_load_dwordx4 v[12:15], v[112:113], off
	global_load_dwordx4 v[36:39], v[112:113], off offset:48
	global_load_dwordx4 v[40:43], v[112:113], off offset:32
	s_nop 1
	v_cmp_gt_u32_e64 s[36:37], s10, v180
	v_or_b32_e32 v178, 7, v187
	s_nop 1
	v_cmp_gt_u32_e64 s[30:31], s10, v178
	s_waitcnt vmcnt(2)
	v_fma_f32 v12, v139, v12, v138
	v_fmac_f32_e32 v12, v140, v13
	s_nop 1
	v_fmac_f32_e32 v12, v141, v14
	v_fmac_f32_e32 v12, v143, v15
	s_nop 1
	v_fmac_f32_e32 v12, v142, v8
	v_fmac_f32_e32 v12, v48, v9
	v_add_f32_e32 v0, 1.0, v2
	v_log_f32_e32 v0, v0
	s_nop 0
	v_mul_f32_e32 v0, 0x3f317218, v0
	s_nop 1
	v_sub_f32_e32 v0, v3, v0
	v_pk_mul_f32 v[8:9], v[66:67], v[10:11]
	v_mul_f32_e32 v0, 0x3d800000, v0
	v_add_f32_e32 v8, v12, v8
	v_cndmask_b32_e64 v0, 0, v0, s[40:41]
	v_add_f32_e32 v10, v8, v9
	s_waitcnt vmcnt(0)
	v_pk_mul_f32 v[8:9], v[68:69], v[40:41]
	v_add_f32_e32 v46, v16, v0
	v_cndmask_b32_e64 v0, 0, v183, s[42:43]
	v_add_f32_e32 v8, v10, v8
	v_add_u32_e32 v114, s54, v0
	v_add_f32_e32 v10, v8, v9
	v_pk_mul_f32 v[8:9], v[64:65], v[42:43]
	v_ashrrev_i32_e32 v115, 31, v114
	v_add_f32_e32 v8, v10, v8
	v_lshlrev_b64 v[0:1], 6, v[114:115]
	v_add_f32_e32 v10, v8, v9
	v_pk_mul_f32 v[8:9], v[72:73], v[36:37]
	v_lshl_add_u64 v[118:119], s[6:7], 0, v[0:1]
	v_add_f32_e32 v8, v10, v8
	global_load_dwordx4 v[74:77], v[118:119], off offset:16
	global_load_dwordx4 v[78:81], v[118:119], off
	global_load_dwordx4 v[82:85], v[118:119], off offset:48
	global_load_dwordx4 v[86:89], v[118:119], off offset:32
	v_add_f32_e32 v10, v8, v9
	v_pk_mul_f32 v[8:9], v[70:71], v[38:39]
	v_cndmask_b32_e64 v0, 0, v180, s[36:37]
	v_add_f32_e32 v8, v10, v8
	v_add_f32_e32 v36, v8, v9
	v_mul_f32_e64 v8, |v36|, s97
	v_exp_f32_e32 v38, v8
	v_min_f32_e32 v39, 0, v36
	v_add_u32_e32 v116, s54, v0
	v_ashrrev_i32_e32 v117, 31, v116
	s_nop 1
	v_lshlrev_b64 v[0:1], 6, v[116:117]
	v_lshl_add_u64 v[122:123], s[6:7], 0, v[0:1]
	s_nop 1
	global_load_dwordx4 v[24:27], v[122:123], off offset:16
	global_load_dwordx4 v[28:31], v[122:123], off
	global_load_dwordx4 v[16:19], v[122:123], off offset:48
	global_load_dwordx4 v[20:23], v[122:123], off offset:32
	s_nop 1
	v_cndmask_b32_e64 v0, 0, v178, s[30:31]
	v_add_u32_e32 v120, s54, v0
	s_nop 1
	v_ashrrev_i32_e32 v121, 31, v120
	v_lshlrev_b64 v[0:1], 6, v[120:121]
	s_nop 1
	v_lshl_add_u64 v[124:125], s[6:7], 0, v[0:1]
	global_load_dwordx4 v[0:3], v[124:125], off offset:16
	global_load_dwordx4 v[4:7], v[124:125], off
	s_nop 1
	global_load_dwordx4 v[8:11], v[124:125], off offset:48
	global_load_dwordx4 v[12:15], v[124:125], off offset:32
	v_add_f32_e32 v36, 1.0, v38
	v_log_f32_e32 v36, v36
	s_nop 0
	v_mul_f32_e32 v36, 0x3f317218, v36
	s_nop 1
	v_sub_f32_e32 v36, v39, v36
	s_waitcnt vmcnt(10)
	v_fma_f32 v39, v139, v78, v138
	v_fmac_f32_e32 v39, v140, v79
	v_fmac_f32_e32 v39, v141, v80
	v_fmac_f32_e32 v39, v143, v81
	v_fmac_f32_e32 v39, v142, v74
	v_mul_f32_e32 v38, 0x3d800000, v36
	v_fmac_f32_e32 v39, v48, v75
	v_pk_mul_f32 v[36:37], v[66:67], v[76:77]
	s_waitcnt vmcnt(6)
	v_fma_f32 v28, v139, v28, v138
	v_add_f32_e32 v36, v39, v36
	v_add_f32_e32 v39, v36, v37
	v_pk_mul_f32 v[36:37], v[68:69], v[86:87]
	v_fmac_f32_e32 v28, v140, v29
	v_add_f32_e32 v36, v39, v36
	v_add_f32_e32 v39, v36, v37
	v_pk_mul_f32 v[36:37], v[64:65], v[88:89]
	v_fmac_f32_e32 v28, v141, v30
	v_add_f32_e32 v36, v39, v36
	v_add_f32_e32 v39, v36, v37
	v_pk_mul_f32 v[36:37], v[72:73], v[82:83]
	v_fmac_f32_e32 v28, v143, v31
	v_add_f32_e32 v36, v39, v36
	v_add_f32_e32 v39, v36, v37
	v_pk_mul_f32 v[36:37], v[70:71], v[84:85]
	v_fmac_f32_e32 v28, v142, v24
	v_add_f32_e32 v36, v39, v36
	v_add_f32_e32 v36, v36, v37
	v_mul_f32_e64 v37, |v36|, s97
	v_exp_f32_e32 v39, v37
	v_cndmask_b32_e64 v37, 0, v38, s[46:47]
	v_min_f32_e32 v40, 0, v36
	v_add_f32_e32 v38, v46, v37
	s_nop 1
	v_fmac_f32_e32 v28, v48, v25
	v_pk_mul_f32 v[24:25], v[66:67], v[26:27]
	s_nop 1
	v_add_f32_e32 v24, v28, v24
	s_nop 1
	v_add_f32_e32 v24, v24, v25
	s_waitcnt vmcnt(4)
	v_pk_mul_f32 v[20:21], v[68:69], v[20:21]
	s_nop 1
	v_add_f32_e32 v20, v24, v20
	s_nop 1
	v_add_f32_e32 v24, v20, v21
	v_pk_mul_f32 v[20:21], v[64:65], v[22:23]
	s_nop 1
	v_add_f32_e32 v20, v24, v20
	s_nop 1
	v_add_f32_e32 v20, v20, v21
	v_pk_mul_f32 v[16:17], v[72:73], v[16:17]
	s_nop 1
	v_add_f32_e32 v16, v20, v16
	s_nop 1
	v_add_f32_e32 v20, v16, v17
	v_pk_mul_f32 v[16:17], v[70:71], v[18:19]
	s_nop 1
	v_add_f32_e32 v16, v20, v16
	s_nop 1
	v_add_f32_e32 v16, v16, v17
	v_mul_f32_e64 v17, |v16|, s97
	s_nop 1
	v_exp_f32_e32 v18, v17
	v_min_f32_e32 v20, 0, v16
	s_nop 1
	s_waitcnt vmcnt(2)
	v_fma_f32 v4, v139, v4, v138
	v_add_f32_e32 v36, 1.0, v39
	v_log_f32_e32 v36, v36
	s_nop 0
	v_mul_f32_e32 v36, 0x3f317218, v36
	s_nop 1
	v_sub_f32_e32 v36, v40, v36
	v_mul_f32_e32 v36, 0x3d800000, v36
	v_cndmask_b32_e64 v17, 0, v36, s[42:43]
	v_add_f32_e32 v19, v38, v17
	s_nop 1
	v_fmac_f32_e32 v4, v140, v5
	v_fmac_f32_e32 v4, v141, v6
	s_nop 1
	v_fmac_f32_e32 v4, v143, v7
	s_nop 1
	v_fmac_f32_e32 v4, v142, v0
	s_nop 1
	v_fmac_f32_e32 v4, v48, v1
	v_pk_mul_f32 v[0:1], v[66:67], v[2:3]
	s_nop 1
	v_add_f32_e32 v0, v4, v0
	v_add_f32_e32 v2, v0, v1
	s_nop 1
	s_waitcnt vmcnt(0)
	v_pk_mul_f32 v[0:1], v[68:69], v[12:13]
	s_nop 1
	v_add_f32_e32 v0, v2, v0
	v_add_f32_e32 v2, v0, v1
	s_nop 1
	v_pk_mul_f32 v[0:1], v[64:65], v[14:15]
	s_nop 0
	v_add_f32_e32 v16, 1.0, v18
	v_log_f32_e32 v16, v16
	s_nop 0
	v_mul_f32_e32 v16, 0x3f317218, v16
	s_nop 1
	v_add_f32_e32 v0, v2, v0
	v_sub_f32_e32 v16, v20, v16
	v_add_f32_e32 v2, v0, v1
	v_pk_mul_f32 v[0:1], v[72:73], v[8:9]
	v_mul_f32_e32 v16, 0x3d800000, v16
	v_add_f32_e32 v0, v2, v0
	v_cndmask_b32_e64 v16, 0, v16, s[36:37]
	v_add_f32_e32 v2, v0, v1
	v_add_f32_e32 v16, v19, v16
	v_pk_mul_f32 v[0:1], v[70:71], v[10:11]
	v_or_b32_e32 v181, 8, v187
	v_add_f32_e32 v0, v2, v0
	v_add_f32_e32 v0, v0, v1
	v_mul_f32_e64 v1, |v0|, s97
	v_exp_f32_e32 v2, v1
	v_min_f32_e32 v3, 0, v0
	v_cmp_gt_u32_e64 s[38:39], s10, v181
	v_or_b32_e32 v179, 9, v187
	s_nop 1
	v_cmp_gt_u32_e64 s[34:35], s10, v179
	v_or_b32_e32 v176, 10, v187
	s_nop 1
	v_cndmask_b32_e64 v0, 0, v181, s[38:39]
	s_nop 1
	v_add_u32_e32 v94, s54, v0
	s_nop 1
	v_ashrrev_i32_e32 v95, 31, v94
	s_nop 1
	v_lshlrev_b64 v[0:1], 6, v[94:95]
	v_lshl_add_u64 v[96:97], s[6:7], 0, v[0:1]
	global_load_dwordx4 v[8:11], v[96:97], off offset:16
	global_load_dwordx4 v[12:15], v[96:97], off
	global_load_dwordx4 v[36:39], v[96:97], off offset:48
	global_load_dwordx4 v[40:43], v[96:97], off offset:32
	s_nop 1
	v_cmp_gt_u32_e64 s[26:27], s10, v176
	v_or_b32_e32 v146, 11, v187
	s_nop 1
	v_cmp_gt_u32_e64 s[22:23], s10, v146
	s_waitcnt vmcnt(2)
	v_fma_f32 v12, v139, v12, v138
	v_fmac_f32_e32 v12, v140, v13
	s_nop 1
	v_fmac_f32_e32 v12, v141, v14
	v_fmac_f32_e32 v12, v143, v15
	s_nop 1
	v_fmac_f32_e32 v12, v142, v8
	v_fmac_f32_e32 v12, v48, v9
	v_add_f32_e32 v0, 1.0, v2
	v_log_f32_e32 v0, v0
	s_nop 0
	v_mul_f32_e32 v0, 0x3f317218, v0
	s_nop 1
	v_sub_f32_e32 v0, v3, v0
	v_pk_mul_f32 v[8:9], v[66:67], v[10:11]
	v_mul_f32_e32 v0, 0x3d800000, v0
	v_add_f32_e32 v8, v12, v8
	v_cndmask_b32_e64 v0, 0, v0, s[30:31]
	v_add_f32_e32 v10, v8, v9
	s_waitcnt vmcnt(0)
	v_pk_mul_f32 v[8:9], v[68:69], v[40:41]
	v_add_f32_e32 v46, v16, v0
	v_cndmask_b32_e64 v0, 0, v179, s[34:35]
	v_add_f32_e32 v8, v10, v8
	v_add_u32_e32 v98, s54, v0
	v_add_f32_e32 v10, v8, v9
	v_pk_mul_f32 v[8:9], v[64:65], v[42:43]
	v_ashrrev_i32_e32 v99, 31, v98
	v_add_f32_e32 v8, v10, v8
	v_lshlrev_b64 v[0:1], 6, v[98:99]
	v_add_f32_e32 v10, v8, v9
	v_pk_mul_f32 v[8:9], v[72:73], v[36:37]
	v_lshl_add_u64 v[102:103], s[6:7], 0, v[0:1]
	v_add_f32_e32 v8, v10, v8
	global_load_dwordx4 v[74:77], v[102:103], off offset:16
	global_load_dwordx4 v[78:81], v[102:103], off
	global_load_dwordx4 v[82:85], v[102:103], off offset:48
	global_load_dwordx4 v[86:89], v[102:103], off offset:32
	v_add_f32_e32 v10, v8, v9
	v_pk_mul_f32 v[8:9], v[70:71], v[38:39]
	v_cndmask_b32_e64 v0, 0, v176, s[26:27]
	v_add_f32_e32 v8, v10, v8
	v_add_f32_e32 v36, v8, v9
	v_mul_f32_e64 v8, |v36|, s97
	v_exp_f32_e32 v38, v8
	v_min_f32_e32 v39, 0, v36
	v_add_u32_e32 v100, s54, v0
	v_ashrrev_i32_e32 v101, 31, v100
	s_nop 1
	v_lshlrev_b64 v[0:1], 6, v[100:101]
	v_lshl_add_u64 v[106:107], s[6:7], 0, v[0:1]
	s_nop 1
	global_load_dwordx4 v[24:27], v[106:107], off offset:16
	global_load_dwordx4 v[28:31], v[106:107], off
	global_load_dwordx4 v[16:19], v[106:107], off offset:48
	global_load_dwordx4 v[20:23], v[106:107], off offset:32
	s_nop 1
	v_cndmask_b32_e64 v0, 0, v146, s[22:23]
	v_add_u32_e32 v104, s54, v0
	s_nop 1
	v_ashrrev_i32_e32 v105, 31, v104
	v_lshlrev_b64 v[0:1], 6, v[104:105]
	s_nop 1
	v_lshl_add_u64 v[108:109], s[6:7], 0, v[0:1]
	global_load_dwordx4 v[0:3], v[108:109], off offset:16
	global_load_dwordx4 v[4:7], v[108:109], off
	s_nop 1
	global_load_dwordx4 v[8:11], v[108:109], off offset:48
	global_load_dwordx4 v[12:15], v[108:109], off offset:32
	v_add_f32_e32 v36, 1.0, v38
	v_log_f32_e32 v36, v36
	s_nop 0
	v_mul_f32_e32 v36, 0x3f317218, v36
	s_nop 1
	v_sub_f32_e32 v36, v39, v36
	s_waitcnt vmcnt(10)
	v_fma_f32 v39, v139, v78, v138
	v_fmac_f32_e32 v39, v140, v79
	v_fmac_f32_e32 v39, v141, v80
	v_fmac_f32_e32 v39, v143, v81
	v_fmac_f32_e32 v39, v142, v74
	v_mul_f32_e32 v38, 0x3d800000, v36
	v_fmac_f32_e32 v39, v48, v75
	v_pk_mul_f32 v[36:37], v[66:67], v[76:77]
	s_waitcnt vmcnt(6)
	v_fma_f32 v28, v139, v28, v138
	v_add_f32_e32 v36, v39, v36
	v_add_f32_e32 v39, v36, v37
	v_pk_mul_f32 v[36:37], v[68:69], v[86:87]
	v_fmac_f32_e32 v28, v140, v29
	v_add_f32_e32 v36, v39, v36
	v_add_f32_e32 v39, v36, v37
	v_pk_mul_f32 v[36:37], v[64:65], v[88:89]
	v_fmac_f32_e32 v28, v141, v30
	v_add_f32_e32 v36, v39, v36
	v_add_f32_e32 v39, v36, v37
	v_pk_mul_f32 v[36:37], v[72:73], v[82:83]
	v_fmac_f32_e32 v28, v143, v31
	v_add_f32_e32 v36, v39, v36
	v_add_f32_e32 v39, v36, v37
	v_pk_mul_f32 v[36:37], v[70:71], v[84:85]
	v_fmac_f32_e32 v28, v142, v24
	v_add_f32_e32 v36, v39, v36
	v_add_f32_e32 v36, v36, v37
	v_mul_f32_e64 v37, |v36|, s97
	v_exp_f32_e32 v39, v37
	v_cndmask_b32_e64 v37, 0, v38, s[38:39]
	v_min_f32_e32 v40, 0, v36
	v_add_f32_e32 v38, v46, v37
	s_nop 1
	v_fmac_f32_e32 v28, v48, v25
	v_pk_mul_f32 v[24:25], v[66:67], v[26:27]
	s_nop 1
	v_add_f32_e32 v24, v28, v24
	s_nop 1
	v_add_f32_e32 v24, v24, v25
	s_waitcnt vmcnt(4)
	v_pk_mul_f32 v[20:21], v[68:69], v[20:21]
	s_nop 1
	v_add_f32_e32 v20, v24, v20
	s_nop 1
	v_add_f32_e32 v24, v20, v21
	v_pk_mul_f32 v[20:21], v[64:65], v[22:23]
	s_nop 1
	v_add_f32_e32 v20, v24, v20
	s_nop 1
	v_add_f32_e32 v20, v20, v21
	v_pk_mul_f32 v[16:17], v[72:73], v[16:17]
	s_nop 1
	v_add_f32_e32 v16, v20, v16
	s_nop 1
	v_add_f32_e32 v20, v16, v17
	v_pk_mul_f32 v[16:17], v[70:71], v[18:19]
	s_nop 1
	v_add_f32_e32 v16, v20, v16
	s_nop 1
	v_add_f32_e32 v16, v16, v17
	v_mul_f32_e64 v17, |v16|, s97
	s_nop 1
	v_exp_f32_e32 v18, v17
	v_min_f32_e32 v20, 0, v16
	s_nop 1
	s_waitcnt vmcnt(2)
	v_fma_f32 v4, v139, v4, v138
	v_add_f32_e32 v36, 1.0, v39
	v_log_f32_e32 v36, v36
	s_nop 0
	v_mul_f32_e32 v36, 0x3f317218, v36
	s_nop 1
	v_sub_f32_e32 v36, v40, v36
	v_mul_f32_e32 v36, 0x3d800000, v36
	v_cndmask_b32_e64 v17, 0, v36, s[34:35]
	v_add_f32_e32 v19, v38, v17
	s_nop 1
	v_fmac_f32_e32 v4, v140, v5
	v_fmac_f32_e32 v4, v141, v6
	s_nop 1
	v_fmac_f32_e32 v4, v143, v7
	s_nop 1
	v_fmac_f32_e32 v4, v142, v0
	s_nop 1
	v_fmac_f32_e32 v4, v48, v1
	v_pk_mul_f32 v[0:1], v[66:67], v[2:3]
	s_nop 1
	v_add_f32_e32 v0, v4, v0
	v_add_f32_e32 v2, v0, v1
	s_nop 1
	s_waitcnt vmcnt(0)
	v_pk_mul_f32 v[0:1], v[68:69], v[12:13]
	s_nop 1
	v_add_f32_e32 v0, v2, v0
	v_add_f32_e32 v2, v0, v1
	s_nop 1
	v_pk_mul_f32 v[0:1], v[64:65], v[14:15]
	s_nop 0
	v_add_f32_e32 v16, 1.0, v18
	v_log_f32_e32 v16, v16
	s_nop 0
	v_mul_f32_e32 v16, 0x3f317218, v16
	s_nop 1
	v_add_f32_e32 v0, v2, v0
	v_sub_f32_e32 v16, v20, v16
	v_add_f32_e32 v2, v0, v1
	v_pk_mul_f32 v[0:1], v[72:73], v[8:9]
	v_mul_f32_e32 v16, 0x3d800000, v16
	v_add_f32_e32 v0, v2, v0
	v_cndmask_b32_e64 v16, 0, v16, s[26:27]
	v_add_f32_e32 v2, v0, v1
	v_add_f32_e32 v16, v19, v16
	v_pk_mul_f32 v[0:1], v[70:71], v[10:11]
	v_or_b32_e32 v177, 12, v187
	v_add_f32_e32 v0, v2, v0
	v_add_f32_e32 v0, v0, v1
	v_mul_f32_e64 v1, |v0|, s97
	v_exp_f32_e32 v2, v1
	v_min_f32_e32 v3, 0, v0
	v_cmp_gt_u32_e64 s[28:29], s10, v177
	v_or_b32_e32 v147, 13, v187
	s_nop 1
	v_cmp_gt_u32_e64 s[24:25], s10, v147
	v_or_b32_e32 v145, 14, v187
	s_nop 1
	v_cndmask_b32_e64 v0, 0, v177, s[28:29]
	s_nop 1
	v_add_u32_e32 v78, s54, v0
	s_nop 1
	v_ashrrev_i32_e32 v79, 31, v78
	s_nop 1
	v_lshlrev_b64 v[0:1], 6, v[78:79]
	v_lshl_add_u64 v[80:81], s[6:7], 0, v[0:1]
	global_load_dwordx4 v[8:11], v[80:81], off offset:16
	global_load_dwordx4 v[12:15], v[80:81], off
	global_load_dwordx4 v[36:39], v[80:81], off offset:48
	global_load_dwordx4 v[40:43], v[80:81], off offset:32
	s_nop 1
	v_cmp_gt_u32_e64 s[20:21], s10, v145
	v_or_b32_e32 v144, 15, v187
	s_nop 1
	s_waitcnt vmcnt(2)
	v_fma_f32 v12, v139, v12, v138
	v_fmac_f32_e32 v12, v140, v13
	s_nop 1
	v_fmac_f32_e32 v12, v141, v14
	v_fmac_f32_e32 v12, v143, v15
	s_nop 1
	v_fmac_f32_e32 v12, v142, v8
	v_fmac_f32_e32 v12, v48, v9
	v_add_f32_e32 v0, 1.0, v2
	v_log_f32_e32 v0, v0
	s_nop 0
	v_mul_f32_e32 v0, 0x3f317218, v0
	s_nop 1
	v_sub_f32_e32 v0, v3, v0
	v_pk_mul_f32 v[8:9], v[66:67], v[10:11]
	v_mul_f32_e32 v0, 0x3d800000, v0
	v_add_f32_e32 v8, v12, v8
	v_cndmask_b32_e64 v0, 0, v0, s[22:23]
	v_add_f32_e32 v10, v8, v9
	s_waitcnt vmcnt(0)
	v_pk_mul_f32 v[8:9], v[68:69], v[40:41]
	v_add_f32_e32 v46, v16, v0
	v_cndmask_b32_e64 v0, 0, v147, s[24:25]
	v_add_f32_e32 v8, v10, v8
	v_add_u32_e32 v82, s54, v0
	v_add_f32_e32 v10, v8, v9
	v_pk_mul_f32 v[8:9], v[64:65], v[42:43]
	v_ashrrev_i32_e32 v83, 31, v82
	v_add_f32_e32 v8, v10, v8
	v_lshlrev_b64 v[0:1], 6, v[82:83]
	v_add_f32_e32 v10, v8, v9
	v_pk_mul_f32 v[8:9], v[72:73], v[36:37]
	v_lshl_add_u64 v[86:87], s[6:7], 0, v[0:1]
	v_add_f32_e32 v8, v10, v8
	global_load_dwordx4 v[74:77], v[86:87], off offset:16
	global_load_dwordx4 v[188:191], v[86:87], off
	global_load_dwordx4 v[192:195], v[86:87], off offset:48
	global_load_dwordx4 v[196:199], v[86:87], off offset:32
	v_add_f32_e32 v10, v8, v9
	v_pk_mul_f32 v[8:9], v[70:71], v[38:39]
	v_cndmask_b32_e64 v0, 0, v145, s[20:21]
	v_add_f32_e32 v8, v10, v8
	v_add_f32_e32 v36, v8, v9
	v_mul_f32_e64 v8, |v36|, s97
	v_exp_f32_e32 v38, v8
	v_min_f32_e32 v39, 0, v36
	v_add_u32_e32 v84, s54, v0
	v_ashrrev_i32_e32 v85, 31, v84
	s_nop 1
	v_lshlrev_b64 v[0:1], 6, v[84:85]
	v_lshl_add_u64 v[90:91], s[6:7], 0, v[0:1]
	s_nop 1
	global_load_dwordx4 v[24:27], v[90:91], off offset:16
	global_load_dwordx4 v[28:31], v[90:91], off
	global_load_dwordx4 v[16:19], v[90:91], off offset:48
	global_load_dwordx4 v[20:23], v[90:91], off offset:32
	s_nop 1
	v_cmp_gt_u32_e32 vcc, s10, v144
	s_waitcnt vmcnt(2)
	v_fma_f32 v28, v139, v28, v138
	s_nop 1
	v_fmac_f32_e32 v28, v140, v29
	v_cndmask_b32_e32 v0, 0, v144, vcc
	s_nop 1
	v_fmac_f32_e32 v28, v141, v30
	v_add_u32_e32 v88, s54, v0
	v_add_f32_e32 v36, 1.0, v38
	v_log_f32_e32 v36, v36
	s_nop 0
	v_mul_f32_e32 v36, 0x3f317218, v36
	s_nop 1
	v_sub_f32_e32 v36, v39, v36
	v_fma_f32 v39, v139, v188, v138
	v_fmac_f32_e32 v39, v140, v189
	v_fmac_f32_e32 v39, v141, v190
	v_fmac_f32_e32 v39, v143, v191
	v_fmac_f32_e32 v39, v142, v74
	v_mul_f32_e32 v38, 0x3d800000, v36
	v_fmac_f32_e32 v39, v48, v75
	v_pk_mul_f32 v[36:37], v[66:67], v[76:77]
	v_fmac_f32_e32 v28, v143, v31
	v_add_f32_e32 v36, v39, v36
	v_add_f32_e32 v39, v36, v37
	v_pk_mul_f32 v[36:37], v[68:69], v[196:197]
	v_ashrrev_i32_e32 v89, 31, v88
	v_add_f32_e32 v36, v39, v36
	v_add_f32_e32 v39, v36, v37
	v_pk_mul_f32 v[36:37], v[64:65], v[198:199]
	v_fmac_f32_e32 v28, v142, v24
	v_add_f32_e32 v36, v39, v36
	v_add_f32_e32 v39, v36, v37
	v_pk_mul_f32 v[36:37], v[72:73], v[192:193]
	v_lshlrev_b64 v[0:1], 6, v[88:89]
	v_add_f32_e32 v36, v39, v36
	v_add_f32_e32 v39, v36, v37
	v_pk_mul_f32 v[36:37], v[70:71], v[194:195]
	v_fmac_f32_e32 v28, v48, v25
	v_add_f32_e32 v36, v39, v36
	v_add_f32_e32 v36, v36, v37
	v_mul_f32_e64 v37, |v36|, s97
	v_exp_f32_e32 v126, v37
	v_cndmask_b32_e64 v37, 0, v38, s[28:29]
	v_min_f32_e32 v188, 0, v36
	v_add_f32_e32 v127, v46, v37
	s_nop 1
	v_pk_mul_f32 v[24:25], v[66:67], v[26:27]
	v_lshl_add_u64 v[92:93], s[6:7], 0, v[0:1]
	s_nop 1
	v_add_f32_e32 v24, v28, v24
	s_nop 1
	global_load_dwordx4 v[0:3], v[92:93], off offset:16
	global_load_dwordx4 v[4:7], v[92:93], off
	s_nop 1
	v_add_f32_e32 v24, v24, v25
	s_nop 1
	s_waitcnt vmcnt(2)
	v_pk_mul_f32 v[20:21], v[68:69], v[20:21]
	s_nop 1
	v_add_f32_e32 v20, v24, v20
	s_nop 1
	v_add_f32_e32 v24, v20, v21
	s_nop 1
	v_pk_mul_f32 v[20:21], v[64:65], v[22:23]
	s_nop 1
	v_add_f32_e32 v20, v24, v20
	s_nop 1
	v_add_f32_e32 v20, v20, v21
	v_pk_mul_f32 v[16:17], v[72:73], v[16:17]
	s_nop 1
	v_add_f32_e32 v16, v20, v16
	s_nop 1
	v_add_f32_e32 v20, v16, v17
	v_pk_mul_f32 v[16:17], v[70:71], v[18:19]
	global_load_dwordx4 v[8:11], v[92:93], off offset:48
	global_load_dwordx4 v[12:15], v[92:93], off offset:32
	s_nop 1
	v_add_f32_e32 v16, v20, v16
	s_nop 1
	v_add_f32_e32 v16, v16, v17
	v_mul_f32_e64 v17, |v16|, s97
	s_nop 1
	v_exp_f32_e32 v30, v17
	s_waitcnt vmcnt(2)
	v_fma_f32 v4, v139, v4, v138
	s_nop 1
	v_fmac_f32_e32 v4, v140, v5
	v_fmac_f32_e32 v4, v141, v6
	v_add_f32_e32 v36, 1.0, v126
	v_log_f32_e32 v36, v36
	s_nop 0
	v_mul_f32_e32 v36, 0x3f317218, v36
	s_nop 1
	v_sub_f32_e32 v36, v188, v36
	v_mul_f32_e32 v36, 0x3d800000, v36
	v_cndmask_b32_e64 v17, 0, v36, s[24:25]
	v_min_f32_e32 v36, 0, v16
	s_nop 1
	v_add_f32_e32 v31, v127, v17
	s_nop 1
	v_fmac_f32_e32 v4, v143, v7
	v_fmac_f32_e32 v4, v142, v0
	s_nop 1
	v_fmac_f32_e32 v4, v48, v1
	s_nop 1
	v_pk_mul_f32 v[0:1], v[66:67], v[2:3]
	s_nop 1
	v_add_f32_e32 v0, v4, v0
	s_nop 1
	v_add_f32_e32 v2, v0, v1
	s_nop 1
	s_waitcnt vmcnt(0)
	v_pk_mul_f32 v[0:1], v[68:69], v[12:13]
	s_nop 1
	v_add_f32_e32 v0, v2, v0
	v_add_f32_e32 v2, v0, v1
	s_nop 1
	v_pk_mul_f32 v[0:1], v[64:65], v[14:15]
	s_nop 2
	v_add_f32_e32 v0, v2, v0
	v_add_f32_e32 v2, v0, v1
	v_add_f32_e32 v16, 1.0, v30
	v_log_f32_e32 v16, v16
	s_nop 0
	v_mul_f32_e32 v16, 0x3f317218, v16
	s_nop 1
	v_sub_f32_e32 v16, v36, v16
	v_pk_mul_f32 v[0:1], v[72:73], v[8:9]
	v_mul_f32_e32 v16, 0x3d800000, v16
	v_add_f32_e32 v0, v2, v0
	v_cndmask_b32_e64 v16, 0, v16, s[20:21]
	v_add_f32_e32 v2, v0, v1
	v_add_f32_e32 v16, v31, v16
	v_pk_mul_f32 v[0:1], v[70:71], v[10:11]
	s_nop 0
	v_add_f32_e32 v0, v2, v0
	v_add_f32_e32 v0, v0, v1
	v_mul_f32_e64 v1, |v0|, s97
	v_exp_f32_e32 v14, v1
	v_min_f32_e32 v15, 0, v0
	s_barrier
	s_nop 7
	s_nop 7
	s_nop 7
	s_nop 6
	v_add_f32_e32 v0, 1.0, v14
	v_log_f32_e32 v0, v0
	s_nop 0
	v_mul_f32_e32 v0, 0x3f317218, v0
	s_nop 1
	v_sub_f32_e32 v0, v15, v0
	v_mul_f32_e32 v0, 0x3d800000, v0
	v_cndmask_b32_e32 v0, 0, v0, vcc
	v_add_f32_e32 v0, v16, v0
	ds_write_b32 v151, v0
	s_waitcnt lgkmcnt(0)
	s_barrier
	ds_read2st64_b32 v[2:3], v159 offset1:1
	ds_read2st64_b32 v[0:1], v159 offset0:2 offset1:3
	s_waitcnt lgkmcnt(1)
	v_add_f32_e32 v2, 0, v2
	s_mov_b64 s[52:53], exec
	v_readlane_b32 s10, v252, 33
	v_readlane_b32 s11, v252, 34
	s_and_b64 s[10:11], s[52:53], s[10:11]
	s_mov_b64 exec, s[10:11]
	s_cbranch_execz .LBB0_278
	s_lshl_b32 s10, s17, 6
	v_add_f32_e32 v4, v2, v3
	s_or_b32 s33, s10, s18
	s_add_i32 s55, s17, 0x3f0
	s_waitcnt lgkmcnt(0)
	v_add_f32_e32 v4, v4, v0
	s_and_b64 s[10:11], s[12:13], exec
	v_add_f32_e32 v4, v4, v1
	s_cselect_b32 s10, s33, s55
	v_mul_f32_e32 v4, 0x3fb8aa3b, v4
	s_mul_hi_i32 s11, s10, 0xc00
	s_mulk_i32 s10, 0xc00
	v_readlane_b32 s33, v252, 44
	v_exp_f32_e32 v4, v4
	s_add_u32 s10, s33, s10
	v_readlane_b32 s33, v252, 45
	s_addc_u32 s11, s33, s11
	s_lshl_b32 s33, s4, 2
	s_add_u32 s10, s10, s33
	v_readlane_b32 s33, v252, 35
	s_addc_u32 s11, s11, 0
	v_lshlrev_b32_e32 v5, 2, v154
	global_store_dword v5, v4, s[10:11]
.LBB0_278:
	s_or_b64 exec, exec, s[52:53]
	v_readlane_b32 s10, v252, 33
	v_readlane_b32 s11, v252, 34
	global_load_dwordx4 v[190:193], v[34:35], off offset:16
	global_load_dwordx4 v[194:197], v[34:35], off
	global_load_dwordx4 v[198:201], v[34:35], off offset:48
	global_load_dwordx4 v[206:209], v[34:35], off offset:32
	v_cndmask_b32_e64 v2, v2, 0, s[10:11]
	v_readlane_b32 s10, v252, 36
	v_add_f32_e32 v3, v3, v2
	v_readlane_b32 s11, v252, 37
	s_lshl_b32 s4, s4, 1
	v_lshl_add_u64 v[126:127], v[54:55], 0, s[4:5]
	v_cndmask_b32_e64 v2, v2, v3, s[10:11]
	v_readlane_b32 s10, v252, 38
	s_waitcnt lgkmcnt(0)
	v_add_f32_e32 v0, v0, v2
	v_readlane_b32 s11, v252, 39
	v_lshl_add_u64 v[74:75], v[56:57], 0, s[4:5]
	v_lshlrev_b64 v[128:129], 9, v[128:129]
	v_cndmask_b32_e64 v0, v2, v0, s[10:11]
	v_readlane_b32 s10, v252, 40
	v_add_f32_e32 v1, v1, v0
	v_readlane_b32 s11, v252, 41
	v_lshl_add_u64 v[76:77], v[58:59], 0, s[4:5]
	s_nop 0
	v_cndmask_b32_e64 v202, v0, v1, s[10:11]
	v_lshlrev_b64 v[0:1], 9, v[32:33]
	v_lshl_add_u64 v[2:3], v[126:127], 0, v[0:1]
	v_lshl_add_u64 v[0:1], v[74:75], 0, v[0:1]
	global_load_ushort v188, v[2:3], off
	global_load_ushort v189, v[0:1], off
	global_load_dwordx4 v[32:35], v[44:45], off offset:48
	global_load_dwordx4 v[36:39], v[44:45], off offset:32
	global_load_dwordx4 v[40:43], v[44:45], off offset:16
	s_nop 0
	global_load_dwordx4 v[44:47], v[44:45], off
	v_lshlrev_b64 v[0:1], 9, v[136:137]
	v_lshl_add_u64 v[2:3], v[126:127], 0, v[0:1]
	v_lshl_add_u64 v[0:1], v[74:75], 0, v[0:1]
	global_load_ushort v136, v[2:3], off
	global_load_ushort v137, v[0:1], off
	global_load_dwordx4 v[16:19], v[134:135], off offset:48
	global_load_dwordx4 v[20:23], v[134:135], off offset:32
	global_load_dwordx4 v[24:27], v[134:135], off offset:16
	global_load_dwordx4 v[28:31], v[134:135], off
	v_lshlrev_b64 v[0:1], 9, v[132:133]
	v_lshl_add_u64 v[2:3], v[126:127], 0, v[0:1]
	v_lshl_add_u64 v[0:1], v[74:75], 0, v[0:1]
	global_load_ushort v132, v[2:3], off
	global_load_ushort v133, v[0:1], off
	s_nop 0
	global_load_dwordx4 v[0:3], v[130:131], off offset:48
	global_load_dwordx4 v[4:7], v[130:131], off offset:32
	global_load_dwordx4 v[8:11], v[130:131], off offset:16
	global_load_dwordx4 v[12:15], v[130:131], off
	v_lshl_add_u64 v[130:131], v[126:127], 0, v[128:129]
	v_lshl_add_u64 v[128:129], v[74:75], 0, v[128:129]
	global_load_ushort v63, v[130:131], off
	s_nop 0
	global_load_ushort v128, v[128:129], off
	s_waitcnt vmcnt(23)
	v_pk_mul_f32 v[130:131], v[66:67], v[192:193]
	s_waitcnt vmcnt(22)
	v_fma_f32 v129, v139, v194, v138
	v_fmac_f32_e32 v129, v140, v195
	v_fmac_f32_e32 v129, v141, v196
	v_fmac_f32_e32 v129, v143, v197
	v_fmac_f32_e32 v129, v142, v190
	v_fmac_f32_e32 v129, v48, v191
	v_add_f32_e32 v129, v129, v130
	v_add_f32_e32 v129, v129, v131
	s_waitcnt vmcnt(20)
	v_pk_mul_f32 v[130:131], v[68:69], v[206:207]
	s_nop 0
	v_add_f32_e32 v129, v129, v130
	v_add_f32_e32 v129, v129, v131
	v_pk_mul_f32 v[130:131], v[64:65], v[208:209]
	s_nop 0
	v_add_f32_e32 v129, v129, v130
	v_add_f32_e32 v129, v129, v131
	v_pk_mul_f32 v[130:131], v[72:73], v[198:199]
	s_nop 0
	v_add_f32_e32 v129, v129, v130
	v_add_f32_e32 v129, v129, v131
	v_pk_mul_f32 v[130:131], v[70:71], v[200:201]
	s_nop 0
	v_add_f32_e32 v129, v129, v130
	v_add_f32_e32 v129, v129, v131
	v_mul_f32_e64 v130, |v129|, s97
	v_exp_f32_e32 v134, v130
	v_min_f32_e32 v129, 0, v129
	s_nop 7
	s_nop 7
	s_nop 3
	v_add_f32_e32 v130, 1.0, v134
	v_log_f32_e32 v130, v130
	s_nop 0
	v_mul_f32_e32 v130, 0x3f317218, v130
	s_nop 1
	v_sub_f32_e32 v129, v129, v130
	v_mul_f32_e32 v129, 0x3d800000, v129
	v_cndmask_b32_e64 v129, 0, v129, s[50:51]
	v_add_f32_e32 v129, v202, v129
	s_and_saveexec_b64 s[52:53], s[50:51]
	s_cbranch_execz .LBB0_280
	v_mul_f32_e32 v135, 0x3fb8aa3b, v129
	v_exp_f32_e32 v135, v135
	v_add_u32_e32 v130, s54, v187
	v_ashrrev_i32_e32 v131, 31, v130
	s_waitcnt vmcnt(18)
	v_lshlrev_b32_e32 v134, 16, v189
	v_mul_f32_e32 v134, v135, v134
	v_lshlrev_b64 v[130:131], 9, v[130:131]
	v_cvt_pk_bf16_f32 v187, v134, v49
	v_lshl_add_u64 v[134:135], v[74:75], 0, v[130:131]
	global_store_short v[134:135], v187, off
	v_mul_f32_e32 v134, 0xbfb8aa3b, v129
	v_exp_f32_e32 v134, v134
	v_lshlrev_b32_e32 v188, 16, v188
	v_lshl_add_u64 v[130:131], v[76:77], 0, v[130:131]
	v_mul_f32_e32 v134, v134, v188
	v_cvt_pk_bf16_f32 v134, v134, v49
	global_store_short v[130:131], v134, off
.LBB0_280:
	s_or_b64 exec, exec, s[52:53]
	s_waitcnt vmcnt(14)
	v_fma_f32 v44, v139, v44, v138
	v_fmac_f32_e32 v44, v140, v45
	v_fmac_f32_e32 v44, v141, v46
	v_fmac_f32_e32 v44, v143, v47
	v_fmac_f32_e32 v44, v142, v40
	v_fmac_f32_e32 v44, v48, v41
	v_pk_mul_f32 v[40:41], v[66:67], v[42:43]
	v_pk_mul_f32 v[36:37], v[68:69], v[36:37]
	v_add_f32_e32 v40, v44, v40
	v_add_f32_e32 v40, v40, v41
	v_add_f32_e32 v36, v40, v36
	v_add_f32_e32 v40, v36, v37
	v_pk_mul_f32 v[36:37], v[64:65], v[38:39]
	v_pk_mul_f32 v[32:33], v[72:73], v[32:33]
	v_add_f32_e32 v36, v40, v36
	v_add_f32_e32 v36, v36, v37
	v_add_f32_e32 v32, v36, v32
	v_add_f32_e32 v36, v32, v33
	v_pk_mul_f32 v[32:33], v[70:71], v[34:35]
	s_nop 0
	v_add_f32_e32 v32, v36, v32
	v_add_f32_e32 v32, v32, v33
	v_mul_f32_e64 v33, |v32|, s97
	v_exp_f32_e32 v34, v33
	v_min_f32_e32 v35, 0, v32
	s_nop 7
	s_nop 7
	s_nop 3
	v_add_f32_e32 v32, 1.0, v34
	v_log_f32_e32 v32, v32
	s_nop 0
	v_mul_f32_e32 v32, 0x3f317218, v32
	s_nop 1
	v_sub_f32_e32 v32, v35, v32
	v_mul_f32_e32 v32, 0x3d800000, v32
	v_cndmask_b32_e64 v32, 0, v32, s[48:49]
	v_add_f32_e32 v32, v129, v32
	s_and_saveexec_b64 s[50:51], s[48:49]
	s_cbranch_execz .LBB0_282
	v_mul_f32_e32 v37, 0x3fb8aa3b, v32
	v_exp_f32_e32 v37, v37
	v_add_u32_e32 v34, s54, v186
	v_ashrrev_i32_e32 v35, 31, v34
	s_waitcnt vmcnt(12)
	v_lshlrev_b32_e32 v36, 16, v137
	v_mul_f32_e32 v36, v37, v36
	v_lshlrev_b64 v[34:35], 9, v[34:35]
	v_cvt_pk_bf16_f32 v38, v36, v49
	v_lshl_add_u64 v[36:37], v[74:75], 0, v[34:35]
	global_store_short v[36:37], v38, off
	v_mul_f32_e32 v36, 0xbfb8aa3b, v32
	v_exp_f32_e32 v36, v36
	v_lshlrev_b32_e32 v33, 16, v136
	v_lshl_add_u64 v[34:35], v[76:77], 0, v[34:35]
	v_mul_f32_e32 v33, v36, v33
	v_cvt_pk_bf16_f32 v33, v33, v49
	global_store_short v[34:35], v33, off
.LBB0_282:
	s_or_b64 exec, exec, s[50:51]
	s_waitcnt vmcnt(8)
	v_fma_f32 v28, v139, v28, v138
	v_fmac_f32_e32 v28, v140, v29
	v_fmac_f32_e32 v28, v141, v30
	v_fmac_f32_e32 v28, v143, v31
	v_fmac_f32_e32 v28, v142, v24
	v_fmac_f32_e32 v28, v48, v25
	v_pk_mul_f32 v[24:25], v[66:67], v[26:27]
	v_pk_mul_f32 v[20:21], v[68:69], v[20:21]
	v_add_f32_e32 v24, v28, v24
	v_add_f32_e32 v24, v24, v25
	v_add_f32_e32 v20, v24, v20
	v_add_f32_e32 v24, v20, v21
	v_pk_mul_f32 v[20:21], v[64:65], v[22:23]
	v_pk_mul_f32 v[16:17], v[72:73], v[16:17]
	v_add_f32_e32 v20, v24, v20
	v_add_f32_e32 v20, v20, v21
	v_add_f32_e32 v16, v20, v16
	v_add_f32_e32 v20, v16, v17
	v_pk_mul_f32 v[16:17], v[70:71], v[18:19]
	s_nop 0
	v_add_f32_e32 v16, v20, v16
	v_add_f32_e32 v16, v16, v17
	v_mul_f32_e64 v17, |v16|, s97
	v_exp_f32_e32 v18, v17
	v_min_f32_e32 v19, 0, v16
	s_nop 7
	s_nop 7
	s_nop 3
	v_add_f32_e32 v16, 1.0, v18
	v_log_f32_e32 v16, v16
	s_nop 0
	v_mul_f32_e32 v16, 0x3f317218, v16
	s_nop 1
	v_sub_f32_e32 v16, v19, v16
	v_mul_f32_e32 v16, 0x3d800000, v16
	v_cndmask_b32_e64 v16, 0, v16, s[44:45]
	v_add_f32_e32 v16, v32, v16
	s_and_saveexec_b64 s[48:49], s[44:45]
	s_cbranch_execz .LBB0_284
	v_mul_f32_e32 v21, 0x3fb8aa3b, v16
	v_exp_f32_e32 v21, v21
	v_add_u32_e32 v18, s54, v184
	v_ashrrev_i32_e32 v19, 31, v18
	s_waitcnt vmcnt(6)
	v_lshlrev_b32_e32 v20, 16, v133
	v_mul_f32_e32 v20, v21, v20
	v_lshlrev_b64 v[18:19], 9, v[18:19]
	v_cvt_pk_bf16_f32 v22, v20, v49
	v_lshl_add_u64 v[20:21], v[74:75], 0, v[18:19]
	global_store_short v[20:21], v22, off
	v_mul_f32_e32 v20, 0xbfb8aa3b, v16
	v_exp_f32_e32 v20, v20
	v_lshlrev_b32_e32 v17, 16, v132
	v_lshl_add_u64 v[18:19], v[76:77], 0, v[18:19]
	v_mul_f32_e32 v17, v20, v17
	v_cvt_pk_bf16_f32 v17, v17, v49
	global_store_short v[18:19], v17, off
.LBB0_284:
	s_or_b64 exec, exec, s[48:49]
	s_waitcnt vmcnt(2)
	v_fma_f32 v12, v139, v12, v138
	v_fmac_f32_e32 v12, v140, v13
	v_fmac_f32_e32 v12, v141, v14
	v_fmac_f32_e32 v12, v143, v15
	v_fmac_f32_e32 v12, v142, v8
	v_fmac_f32_e32 v12, v48, v9
	v_pk_mul_f32 v[8:9], v[66:67], v[10:11]
	v_pk_mul_f32 v[4:5], v[68:69], v[4:5]
	v_add_f32_e32 v8, v12, v8
	v_add_f32_e32 v8, v8, v9
	v_add_f32_e32 v4, v8, v4
	v_add_f32_e32 v8, v4, v5
	v_pk_mul_f32 v[4:5], v[64:65], v[6:7]
	v_pk_mul_f32 v[0:1], v[72:73], v[0:1]
	v_add_f32_e32 v4, v8, v4
	v_add_f32_e32 v4, v4, v5
	v_add_f32_e32 v0, v4, v0
	v_add_f32_e32 v4, v0, v1
	v_pk_mul_f32 v[0:1], v[70:71], v[2:3]
	s_nop 0
	v_add_f32_e32 v0, v4, v0
	v_add_f32_e32 v0, v0, v1
	v_mul_f32_e64 v1, |v0|, s97
	v_exp_f32_e32 v2, v1
	v_min_f32_e32 v3, 0, v0
	s_nop 7
	s_nop 7
	s_nop 3
	v_add_f32_e32 v0, 1.0, v2
	v_log_f32_e32 v0, v0
	s_nop 0
	v_mul_f32_e32 v0, 0x3f317218, v0
	s_nop 1
	v_sub_f32_e32 v0, v3, v0
	v_mul_f32_e32 v0, 0x3d800000, v0
	v_cndmask_b32_e64 v0, 0, v0, s[40:41]
	v_add_f32_e32 v129, v16, v0
	s_and_saveexec_b64 s[44:45], s[40:41]
	s_cbranch_execz .LBB0_286
	v_mul_f32_e32 v3, 0x3fb8aa3b, v129
	v_exp_f32_e32 v3, v3
	v_add_u32_e32 v0, s54, v182
	v_ashrrev_i32_e32 v1, 31, v0
	s_waitcnt vmcnt(0)
	v_lshlrev_b32_e32 v2, 16, v128
	v_mul_f32_e32 v2, v3, v2
	v_lshlrev_b64 v[0:1], 9, v[0:1]
	v_cvt_pk_bf16_f32 v5, v2, v49
	v_lshl_add_u64 v[2:3], v[74:75], 0, v[0:1]
	global_store_short v[2:3], v5, off
	v_mul_f32_e32 v2, 0xbfb8aa3b, v129
	v_exp_f32_e32 v2, v2
	v_lshlrev_b32_e32 v4, 16, v63
	v_lshl_add_u64 v[0:1], v[76:77], 0, v[0:1]
	v_mul_f32_e32 v2, v2, v4
	v_cvt_pk_bf16_f32 v2, v2, v49
	global_store_short v[0:1], v2, off
.LBB0_286:
	s_or_b64 exec, exec, s[44:45]
	global_load_dwordx4 v[132:135], v[112:113], off offset:16
	global_load_dwordx4 v[186:189], v[112:113], off
	global_load_dwordx4 v[190:193], v[112:113], off offset:48
	global_load_dwordx4 v[194:197], v[112:113], off offset:32
	v_lshlrev_b64 v[0:1], 9, v[110:111]
	v_lshl_add_u64 v[2:3], v[126:127], 0, v[0:1]
	v_lshl_add_u64 v[0:1], v[74:75], 0, v[0:1]
	global_load_ushort v128, v[2:3], off
	global_load_ushort v130, v[0:1], off
	global_load_dwordx4 v[32:35], v[118:119], off offset:48
	global_load_dwordx4 v[36:39], v[118:119], off offset:32
	global_load_dwordx4 v[40:43], v[118:119], off offset:16
	global_load_dwordx4 v[44:47], v[118:119], off
	v_lshlrev_b64 v[0:1], 9, v[114:115]
	v_lshl_add_u64 v[2:3], v[126:127], 0, v[0:1]
	v_lshl_add_u64 v[0:1], v[74:75], 0, v[0:1]
	global_load_ushort v113, v[2:3], off
	global_load_ushort v114, v[0:1], off
	global_load_dwordx4 v[16:19], v[122:123], off offset:48
	global_load_dwordx4 v[20:23], v[122:123], off offset:32
	global_load_dwordx4 v[24:27], v[122:123], off offset:16
	global_load_dwordx4 v[28:31], v[122:123], off
	v_lshlrev_b64 v[0:1], 9, v[116:117]
	v_lshl_add_u64 v[2:3], v[126:127], 0, v[0:1]
	v_lshl_add_u64 v[0:1], v[74:75], 0, v[0:1]
	global_load_ushort v111, v[2:3], off
	global_load_ushort v112, v[0:1], off
	s_nop 0
	global_load_dwordx4 v[0:3], v[124:125], off offset:48
	global_load_dwordx4 v[4:7], v[124:125], off offset:32
	global_load_dwordx4 v[8:11], v[124:125], off offset:16
	global_load_dwordx4 v[12:15], v[124:125], off
	v_lshlrev_b64 v[116:117], 9, v[120:121]
	v_lshl_add_u64 v[118:119], v[126:127], 0, v[116:117]
	v_lshl_add_u64 v[116:117], v[74:75], 0, v[116:117]
	global_load_ushort v63, v[118:119], off
	global_load_ushort v110, v[116:117], off
	s_waitcnt vmcnt(23)
	v_pk_mul_f32 v[116:117], v[66:67], v[134:135]
	s_waitcnt vmcnt(22)
	v_fma_f32 v115, v139, v186, v138
	v_fmac_f32_e32 v115, v140, v187
	v_fmac_f32_e32 v115, v141, v188
	v_fmac_f32_e32 v115, v143, v189
	v_fmac_f32_e32 v115, v142, v132
	v_fmac_f32_e32 v115, v48, v133
	v_add_f32_e32 v115, v115, v116
	v_add_f32_e32 v115, v115, v117
	s_waitcnt vmcnt(20)
	v_pk_mul_f32 v[116:117], v[68:69], v[194:195]
	s_nop 0
	v_add_f32_e32 v115, v115, v116
	v_add_f32_e32 v115, v115, v117
	v_pk_mul_f32 v[116:117], v[64:65], v[196:197]
	s_nop 0
	v_add_f32_e32 v115, v115, v116
	v_add_f32_e32 v115, v115, v117
	v_pk_mul_f32 v[116:117], v[72:73], v[190:191]
	s_nop 0
	v_add_f32_e32 v115, v115, v116
	v_add_f32_e32 v115, v115, v117
	v_pk_mul_f32 v[116:117], v[70:71], v[192:193]
	s_nop 0
	v_add_f32_e32 v115, v115, v116
	v_add_f32_e32 v115, v115, v117
	v_mul_f32_e64 v116, |v115|, s97
	v_exp_f32_e32 v118, v116
	v_min_f32_e32 v115, 0, v115
	s_nop 7
	s_nop 7
	s_nop 3
	v_add_f32_e32 v116, 1.0, v118
	v_log_f32_e32 v116, v116
	s_nop 0
	v_mul_f32_e32 v116, 0x3f317218, v116
	s_nop 1
	v_sub_f32_e32 v115, v115, v116
	v_mul_f32_e32 v115, 0x3d800000, v115
	v_cndmask_b32_e64 v115, 0, v115, s[46:47]
	v_add_f32_e32 v115, v129, v115
	s_and_saveexec_b64 s[40:41], s[46:47]
	s_cbranch_execz .LBB0_288
	v_mul_f32_e32 v119, 0x3fb8aa3b, v115
	v_exp_f32_e32 v119, v119
	v_add_u32_e32 v116, s54, v185
	v_ashrrev_i32_e32 v117, 31, v116
	s_waitcnt vmcnt(18)
	v_lshlrev_b32_e32 v118, 16, v130
	v_mul_f32_e32 v118, v119, v118
	v_lshlrev_b64 v[116:117], 9, v[116:117]
	v_cvt_pk_bf16_f32 v121, v118, v49
	v_lshl_add_u64 v[118:119], v[74:75], 0, v[116:117]
	global_store_short v[118:119], v121, off
	v_mul_f32_e32 v118, 0xbfb8aa3b, v115
	v_exp_f32_e32 v118, v118
	v_lshlrev_b32_e32 v120, 16, v128
	v_lshl_add_u64 v[116:117], v[76:77], 0, v[116:117]
	v_mul_f32_e32 v118, v118, v120
	v_cvt_pk_bf16_f32 v118, v118, v49
	global_store_short v[116:117], v118, off
.LBB0_288:
	s_or_b64 exec, exec, s[40:41]
	s_waitcnt vmcnt(14)
	v_fma_f32 v44, v139, v44, v138
	v_fmac_f32_e32 v44, v140, v45
	v_fmac_f32_e32 v44, v141, v46
	v_fmac_f32_e32 v44, v143, v47
	v_fmac_f32_e32 v44, v142, v40
	v_fmac_f32_e32 v44, v48, v41
	v_pk_mul_f32 v[40:41], v[66:67], v[42:43]
	v_pk_mul_f32 v[36:37], v[68:69], v[36:37]
	v_add_f32_e32 v40, v44, v40
	v_add_f32_e32 v40, v40, v41
	v_add_f32_e32 v36, v40, v36
	v_add_f32_e32 v40, v36, v37
	v_pk_mul_f32 v[36:37], v[64:65], v[38:39]
	v_pk_mul_f32 v[32:33], v[72:73], v[32:33]
	v_add_f32_e32 v36, v40, v36
	v_add_f32_e32 v36, v36, v37
	v_add_f32_e32 v32, v36, v32
	v_add_f32_e32 v36, v32, v33
	v_pk_mul_f32 v[32:33], v[70:71], v[34:35]
	s_nop 0
	v_add_f32_e32 v32, v36, v32
	v_add_f32_e32 v32, v32, v33
	v_mul_f32_e64 v33, |v32|, s97
	v_exp_f32_e32 v34, v33
	v_min_f32_e32 v35, 0, v32
	s_nop 7
	s_nop 7
	s_nop 3
	v_add_f32_e32 v32, 1.0, v34
	v_log_f32_e32 v32, v32
	s_nop 0
	v_mul_f32_e32 v32, 0x3f317218, v32
	s_nop 1
	v_sub_f32_e32 v32, v35, v32
	v_mul_f32_e32 v32, 0x3d800000, v32
	v_cndmask_b32_e64 v32, 0, v32, s[42:43]
	v_add_f32_e32 v32, v115, v32
	s_and_saveexec_b64 s[40:41], s[42:43]
	s_cbranch_execz .LBB0_290
	v_mul_f32_e32 v37, 0x3fb8aa3b, v32
	v_exp_f32_e32 v37, v37
	v_add_u32_e32 v34, s54, v183
	v_ashrrev_i32_e32 v35, 31, v34
	s_waitcnt vmcnt(12)
	v_lshlrev_b32_e32 v36, 16, v114
	v_mul_f32_e32 v36, v37, v36
	v_lshlrev_b64 v[34:35], 9, v[34:35]
	v_cvt_pk_bf16_f32 v38, v36, v49
	v_lshl_add_u64 v[36:37], v[74:75], 0, v[34:35]
	global_store_short v[36:37], v38, off
	v_mul_f32_e32 v36, 0xbfb8aa3b, v32
	v_exp_f32_e32 v36, v36
	v_lshlrev_b32_e32 v33, 16, v113
	v_lshl_add_u64 v[34:35], v[76:77], 0, v[34:35]
	v_mul_f32_e32 v33, v36, v33
	v_cvt_pk_bf16_f32 v33, v33, v49
	global_store_short v[34:35], v33, off
.LBB0_290:
	s_or_b64 exec, exec, s[40:41]
	s_waitcnt vmcnt(8)
	v_fma_f32 v28, v139, v28, v138
	v_fmac_f32_e32 v28, v140, v29
	v_fmac_f32_e32 v28, v141, v30
	v_fmac_f32_e32 v28, v143, v31
	v_fmac_f32_e32 v28, v142, v24
	v_fmac_f32_e32 v28, v48, v25
	v_pk_mul_f32 v[24:25], v[66:67], v[26:27]
	v_pk_mul_f32 v[20:21], v[68:69], v[20:21]
	v_add_f32_e32 v24, v28, v24
	v_add_f32_e32 v24, v24, v25
	v_add_f32_e32 v20, v24, v20
	v_add_f32_e32 v24, v20, v21
	v_pk_mul_f32 v[20:21], v[64:65], v[22:23]
	v_pk_mul_f32 v[16:17], v[72:73], v[16:17]
	v_add_f32_e32 v20, v24, v20
	v_add_f32_e32 v20, v20, v21
	v_add_f32_e32 v16, v20, v16
	v_add_f32_e32 v20, v16, v17
	v_pk_mul_f32 v[16:17], v[70:71], v[18:19]
	s_nop 0
	v_add_f32_e32 v16, v20, v16
	v_add_f32_e32 v16, v16, v17
	v_mul_f32_e64 v17, |v16|, s97
	v_exp_f32_e32 v18, v17
	v_min_f32_e32 v19, 0, v16
	s_nop 7
	s_nop 7
	s_nop 3
	v_add_f32_e32 v16, 1.0, v18
	v_log_f32_e32 v16, v16
	s_nop 0
	v_mul_f32_e32 v16, 0x3f317218, v16
	s_nop 1
	v_sub_f32_e32 v16, v19, v16
	v_mul_f32_e32 v16, 0x3d800000, v16
	v_cndmask_b32_e64 v16, 0, v16, s[36:37]
	v_add_f32_e32 v16, v32, v16
	s_and_saveexec_b64 s[40:41], s[36:37]
	s_cbranch_execz .LBB0_292
	v_mul_f32_e32 v21, 0x3fb8aa3b, v16
	v_exp_f32_e32 v21, v21
	v_add_u32_e32 v18, s54, v180
	v_ashrrev_i32_e32 v19, 31, v18
	s_waitcnt vmcnt(6)
	v_lshlrev_b32_e32 v20, 16, v112
	v_mul_f32_e32 v20, v21, v20
	v_lshlrev_b64 v[18:19], 9, v[18:19]
	v_cvt_pk_bf16_f32 v22, v20, v49
	v_lshl_add_u64 v[20:21], v[74:75], 0, v[18:19]
	global_store_short v[20:21], v22, off
	v_mul_f32_e32 v20, 0xbfb8aa3b, v16
	v_exp_f32_e32 v20, v20
	v_lshlrev_b32_e32 v17, 16, v111
	v_lshl_add_u64 v[18:19], v[76:77], 0, v[18:19]
	v_mul_f32_e32 v17, v20, v17
	v_cvt_pk_bf16_f32 v17, v17, v49
	global_store_short v[18:19], v17, off
.LBB0_292:
	s_or_b64 exec, exec, s[40:41]
	s_waitcnt vmcnt(2)
	v_fma_f32 v12, v139, v12, v138
	v_fmac_f32_e32 v12, v140, v13
	v_fmac_f32_e32 v12, v141, v14
	v_fmac_f32_e32 v12, v143, v15
	v_fmac_f32_e32 v12, v142, v8
	v_fmac_f32_e32 v12, v48, v9
	v_pk_mul_f32 v[8:9], v[66:67], v[10:11]
	v_pk_mul_f32 v[4:5], v[68:69], v[4:5]
	v_add_f32_e32 v8, v12, v8
	v_add_f32_e32 v8, v8, v9
	v_add_f32_e32 v4, v8, v4
	v_add_f32_e32 v8, v4, v5
	v_pk_mul_f32 v[4:5], v[64:65], v[6:7]
	v_pk_mul_f32 v[0:1], v[72:73], v[0:1]
	v_add_f32_e32 v4, v8, v4
	v_add_f32_e32 v4, v4, v5
	v_add_f32_e32 v0, v4, v0
	v_add_f32_e32 v4, v0, v1
	v_pk_mul_f32 v[0:1], v[70:71], v[2:3]
	s_nop 0
	v_add_f32_e32 v0, v4, v0
	v_add_f32_e32 v0, v0, v1
	v_mul_f32_e64 v1, |v0|, s97
	v_exp_f32_e32 v2, v1
	v_min_f32_e32 v3, 0, v0
	s_nop 7
	s_nop 7
	s_nop 3
	v_add_f32_e32 v0, 1.0, v2
	v_log_f32_e32 v0, v0
	s_nop 0
	v_mul_f32_e32 v0, 0x3f317218, v0
	s_nop 1
	v_sub_f32_e32 v0, v3, v0
	v_mul_f32_e32 v0, 0x3d800000, v0
	v_cndmask_b32_e64 v0, 0, v0, s[30:31]
	v_add_f32_e32 v111, v16, v0
	s_and_saveexec_b64 s[36:37], s[30:31]
	s_cbranch_execz .LBB0_294
	v_mul_f32_e32 v3, 0x3fb8aa3b, v111
	v_exp_f32_e32 v3, v3
	v_add_u32_e32 v0, s54, v178
	v_ashrrev_i32_e32 v1, 31, v0
	s_waitcnt vmcnt(0)
	v_lshlrev_b32_e32 v2, 16, v110
	v_mul_f32_e32 v2, v3, v2
	v_lshlrev_b64 v[0:1], 9, v[0:1]
	v_cvt_pk_bf16_f32 v5, v2, v49
	v_lshl_add_u64 v[2:3], v[74:75], 0, v[0:1]
	global_store_short v[2:3], v5, off
	v_mul_f32_e32 v2, 0xbfb8aa3b, v111
	v_exp_f32_e32 v2, v2
	v_lshlrev_b32_e32 v4, 16, v63
	v_lshl_add_u64 v[0:1], v[76:77], 0, v[0:1]
	v_mul_f32_e32 v2, v2, v4
	v_cvt_pk_bf16_f32 v2, v2, v49
	global_store_short v[0:1], v2, off
.LBB0_294:
	s_or_b64 exec, exec, s[36:37]
	global_load_dwordx4 v[114:117], v[96:97], off offset:16
	global_load_dwordx4 v[118:121], v[96:97], off
	global_load_dwordx4 v[122:125], v[96:97], off offset:48
	global_load_dwordx4 v[128:131], v[96:97], off offset:32
	v_lshlrev_b64 v[0:1], 9, v[94:95]
	v_lshl_add_u64 v[2:3], v[126:127], 0, v[0:1]
	v_lshl_add_u64 v[0:1], v[74:75], 0, v[0:1]
	global_load_ushort v110, v[2:3], off
	global_load_ushort v112, v[0:1], off
	global_load_dwordx4 v[32:35], v[102:103], off offset:48
	global_load_dwordx4 v[36:39], v[102:103], off offset:32
	global_load_dwordx4 v[40:43], v[102:103], off offset:16
	global_load_dwordx4 v[44:47], v[102:103], off
	v_lshlrev_b64 v[0:1], 9, v[98:99]
	v_lshl_add_u64 v[2:3], v[126:127], 0, v[0:1]
	v_lshl_add_u64 v[0:1], v[74:75], 0, v[0:1]
	global_load_ushort v97, v[2:3], off
	global_load_ushort v98, v[0:1], off
	global_load_dwordx4 v[16:19], v[106:107], off offset:48
	global_load_dwordx4 v[20:23], v[106:107], off offset:32
	global_load_dwordx4 v[24:27], v[106:107], off offset:16
	global_load_dwordx4 v[28:31], v[106:107], off
	v_lshlrev_b64 v[0:1], 9, v[100:101]
	v_lshl_add_u64 v[2:3], v[126:127], 0, v[0:1]
	v_lshl_add_u64 v[0:1], v[74:75], 0, v[0:1]
	global_load_ushort v95, v[2:3], off
	global_load_ushort v96, v[0:1], off
	s_nop 0
	global_load_dwordx4 v[0:3], v[108:109], off offset:48
	global_load_dwordx4 v[4:7], v[108:109], off offset:32
	global_load_dwordx4 v[8:11], v[108:109], off offset:16
	global_load_dwordx4 v[12:15], v[108:109], off
	v_lshlrev_b64 v[100:101], 9, v[104:105]
	v_lshl_add_u64 v[102:103], v[126:127], 0, v[100:101]
	v_lshl_add_u64 v[100:101], v[74:75], 0, v[100:101]
	global_load_ushort v63, v[102:103], off
	global_load_ushort v94, v[100:101], off
	s_waitcnt vmcnt(23)
	v_pk_mul_f32 v[100:101], v[66:67], v[116:117]
	s_waitcnt vmcnt(22)
	v_fma_f32 v99, v139, v118, v138
	v_fmac_f32_e32 v99, v140, v119
	v_fmac_f32_e32 v99, v141, v120
	v_fmac_f32_e32 v99, v143, v121
	v_fmac_f32_e32 v99, v142, v114
	v_fmac_f32_e32 v99, v48, v115
	v_add_f32_e32 v99, v99, v100
	v_add_f32_e32 v99, v99, v101
	s_waitcnt vmcnt(20)
	v_pk_mul_f32 v[100:101], v[68:69], v[128:129]
	s_nop 0
	v_add_f32_e32 v99, v99, v100
	v_add_f32_e32 v99, v99, v101
	v_pk_mul_f32 v[100:101], v[64:65], v[130:131]
	s_nop 0
	v_add_f32_e32 v99, v99, v100
	v_add_f32_e32 v99, v99, v101
	v_pk_mul_f32 v[100:101], v[72:73], v[122:123]
	s_nop 0
	v_add_f32_e32 v99, v99, v100
	v_add_f32_e32 v99, v99, v101
	v_pk_mul_f32 v[100:101], v[70:71], v[124:125]
	s_nop 0
	v_add_f32_e32 v99, v99, v100
	v_add_f32_e32 v99, v99, v101
	v_mul_f32_e64 v100, |v99|, s97
	v_exp_f32_e32 v102, v100
	v_min_f32_e32 v99, 0, v99
	s_nop 7
	s_nop 7
	s_nop 3
	v_add_f32_e32 v100, 1.0, v102
	v_log_f32_e32 v100, v100
	s_nop 0
	v_mul_f32_e32 v100, 0x3f317218, v100
	s_nop 1
	v_sub_f32_e32 v99, v99, v100
	v_mul_f32_e32 v99, 0x3d800000, v99
	v_cndmask_b32_e64 v99, 0, v99, s[38:39]
	v_add_f32_e32 v99, v111, v99
	s_and_saveexec_b64 s[30:31], s[38:39]
	s_cbranch_execz .LBB0_296
	v_mul_f32_e32 v103, 0x3fb8aa3b, v99
	v_exp_f32_e32 v103, v103
	v_add_u32_e32 v100, s54, v181
	v_ashrrev_i32_e32 v101, 31, v100
	s_waitcnt vmcnt(18)
	v_lshlrev_b32_e32 v102, 16, v112
	v_mul_f32_e32 v102, v103, v102
	v_lshlrev_b64 v[100:101], 9, v[100:101]
	v_cvt_pk_bf16_f32 v105, v102, v49
	v_lshl_add_u64 v[102:103], v[74:75], 0, v[100:101]
	global_store_short v[102:103], v105, off
	v_mul_f32_e32 v102, 0xbfb8aa3b, v99
	v_exp_f32_e32 v102, v102
	v_lshlrev_b32_e32 v104, 16, v110
	v_lshl_add_u64 v[100:101], v[76:77], 0, v[100:101]
	v_mul_f32_e32 v102, v102, v104
	v_cvt_pk_bf16_f32 v102, v102, v49
	global_store_short v[100:101], v102, off
.LBB0_296:
	s_or_b64 exec, exec, s[30:31]
	s_waitcnt vmcnt(14)
	v_fma_f32 v44, v139, v44, v138
	v_fmac_f32_e32 v44, v140, v45
	v_fmac_f32_e32 v44, v141, v46
	v_fmac_f32_e32 v44, v143, v47
	v_fmac_f32_e32 v44, v142, v40
	v_fmac_f32_e32 v44, v48, v41
	v_pk_mul_f32 v[40:41], v[66:67], v[42:43]
	v_pk_mul_f32 v[36:37], v[68:69], v[36:37]
	v_add_f32_e32 v40, v44, v40
	v_add_f32_e32 v40, v40, v41
	v_add_f32_e32 v36, v40, v36
	v_add_f32_e32 v40, v36, v37
	v_pk_mul_f32 v[36:37], v[64:65], v[38:39]
	v_pk_mul_f32 v[32:33], v[72:73], v[32:33]
	v_add_f32_e32 v36, v40, v36
	v_add_f32_e32 v36, v36, v37
	v_add_f32_e32 v32, v36, v32
	v_add_f32_e32 v36, v32, v33
	v_pk_mul_f32 v[32:33], v[70:71], v[34:35]
	s_nop 0
	v_add_f32_e32 v32, v36, v32
	v_add_f32_e32 v32, v32, v33
	v_mul_f32_e64 v33, |v32|, s97
	v_exp_f32_e32 v34, v33
	v_min_f32_e32 v35, 0, v32
	s_nop 7
	s_nop 7
	s_nop 3
	v_add_f32_e32 v32, 1.0, v34
	v_log_f32_e32 v32, v32
	s_nop 0
	v_mul_f32_e32 v32, 0x3f317218, v32
	s_nop 1
	v_sub_f32_e32 v32, v35, v32
	v_mul_f32_e32 v32, 0x3d800000, v32
	v_cndmask_b32_e64 v32, 0, v32, s[34:35]
	v_add_f32_e32 v32, v99, v32
	s_and_saveexec_b64 s[30:31], s[34:35]
	s_cbranch_execz .LBB0_298
	v_mul_f32_e32 v37, 0x3fb8aa3b, v32
	v_exp_f32_e32 v37, v37
	v_add_u32_e32 v34, s54, v179
	v_ashrrev_i32_e32 v35, 31, v34
	s_waitcnt vmcnt(12)
	v_lshlrev_b32_e32 v36, 16, v98
	v_mul_f32_e32 v36, v37, v36
	v_lshlrev_b64 v[34:35], 9, v[34:35]
	v_cvt_pk_bf16_f32 v38, v36, v49
	v_lshl_add_u64 v[36:37], v[74:75], 0, v[34:35]
	global_store_short v[36:37], v38, off
	v_mul_f32_e32 v36, 0xbfb8aa3b, v32
	v_exp_f32_e32 v36, v36
	v_lshlrev_b32_e32 v33, 16, v97
	v_lshl_add_u64 v[34:35], v[76:77], 0, v[34:35]
	v_mul_f32_e32 v33, v36, v33
	v_cvt_pk_bf16_f32 v33, v33, v49
	global_store_short v[34:35], v33, off
.LBB0_298:
	s_or_b64 exec, exec, s[30:31]
	s_waitcnt vmcnt(8)
	v_fma_f32 v28, v139, v28, v138
	v_fmac_f32_e32 v28, v140, v29
	v_fmac_f32_e32 v28, v141, v30
	v_fmac_f32_e32 v28, v143, v31
	v_fmac_f32_e32 v28, v142, v24
	v_fmac_f32_e32 v28, v48, v25
	v_pk_mul_f32 v[24:25], v[66:67], v[26:27]
	v_pk_mul_f32 v[20:21], v[68:69], v[20:21]
	v_add_f32_e32 v24, v28, v24
	v_add_f32_e32 v24, v24, v25
	v_add_f32_e32 v20, v24, v20
	v_add_f32_e32 v24, v20, v21
	v_pk_mul_f32 v[20:21], v[64:65], v[22:23]
	v_pk_mul_f32 v[16:17], v[72:73], v[16:17]
	v_add_f32_e32 v20, v24, v20
	v_add_f32_e32 v20, v20, v21
	v_add_f32_e32 v16, v20, v16
	v_add_f32_e32 v20, v16, v17
	v_pk_mul_f32 v[16:17], v[70:71], v[18:19]
	s_nop 0
	v_add_f32_e32 v16, v20, v16
	v_add_f32_e32 v16, v16, v17
	v_mul_f32_e64 v17, |v16|, s97
	v_exp_f32_e32 v18, v17
	v_min_f32_e32 v19, 0, v16
	s_nop 7
	s_nop 7
	s_nop 3
	v_add_f32_e32 v16, 1.0, v18
	v_log_f32_e32 v16, v16
	s_nop 0
	v_mul_f32_e32 v16, 0x3f317218, v16
	s_nop 1
	v_sub_f32_e32 v16, v19, v16
	v_mul_f32_e32 v16, 0x3d800000, v16
	v_cndmask_b32_e64 v16, 0, v16, s[26:27]
	v_add_f32_e32 v16, v32, v16
	s_and_saveexec_b64 s[30:31], s[26:27]
	s_cbranch_execz .LBB0_300
	v_mul_f32_e32 v21, 0x3fb8aa3b, v16
	v_exp_f32_e32 v21, v21
	v_add_u32_e32 v18, s54, v176
	v_ashrrev_i32_e32 v19, 31, v18
	s_waitcnt vmcnt(6)
	v_lshlrev_b32_e32 v20, 16, v96
	v_mul_f32_e32 v20, v21, v20
	v_lshlrev_b64 v[18:19], 9, v[18:19]
	v_cvt_pk_bf16_f32 v22, v20, v49
	v_lshl_add_u64 v[20:21], v[74:75], 0, v[18:19]
	global_store_short v[20:21], v22, off
	v_mul_f32_e32 v20, 0xbfb8aa3b, v16
	v_exp_f32_e32 v20, v20
	v_lshlrev_b32_e32 v17, 16, v95
	v_lshl_add_u64 v[18:19], v[76:77], 0, v[18:19]
	v_mul_f32_e32 v17, v20, v17
	v_cvt_pk_bf16_f32 v17, v17, v49
	global_store_short v[18:19], v17, off
.LBB0_300:
	s_or_b64 exec, exec, s[30:31]
	s_waitcnt vmcnt(2)
	v_fma_f32 v12, v139, v12, v138
	v_fmac_f32_e32 v12, v140, v13
	v_fmac_f32_e32 v12, v141, v14
	v_fmac_f32_e32 v12, v143, v15
	v_fmac_f32_e32 v12, v142, v8
	v_fmac_f32_e32 v12, v48, v9
	v_pk_mul_f32 v[8:9], v[66:67], v[10:11]
	v_pk_mul_f32 v[4:5], v[68:69], v[4:5]
	v_add_f32_e32 v8, v12, v8
	v_add_f32_e32 v8, v8, v9
	v_add_f32_e32 v4, v8, v4
	v_add_f32_e32 v8, v4, v5
	v_pk_mul_f32 v[4:5], v[64:65], v[6:7]
	v_pk_mul_f32 v[0:1], v[72:73], v[0:1]
	v_add_f32_e32 v4, v8, v4
	v_add_f32_e32 v4, v4, v5
	v_add_f32_e32 v0, v4, v0
	v_add_f32_e32 v4, v0, v1
	v_pk_mul_f32 v[0:1], v[70:71], v[2:3]
	s_nop 0
	v_add_f32_e32 v0, v4, v0
	v_add_f32_e32 v0, v0, v1
	v_mul_f32_e64 v1, |v0|, s97
	v_exp_f32_e32 v2, v1
	v_min_f32_e32 v3, 0, v0
	s_nop 7
	s_nop 7
	s_nop 3
	v_add_f32_e32 v0, 1.0, v2
	v_log_f32_e32 v0, v0
	s_nop 0
	v_mul_f32_e32 v0, 0x3f317218, v0
	s_nop 1
	v_sub_f32_e32 v0, v3, v0
	v_mul_f32_e32 v0, 0x3d800000, v0
	v_cndmask_b32_e64 v0, 0, v0, s[22:23]
	v_add_f32_e32 v95, v16, v0
	s_and_saveexec_b64 s[26:27], s[22:23]
	s_cbranch_execz .LBB0_302
	v_mul_f32_e32 v3, 0x3fb8aa3b, v95
	v_exp_f32_e32 v3, v3
	v_add_u32_e32 v0, s54, v146
	v_ashrrev_i32_e32 v1, 31, v0
	s_waitcnt vmcnt(0)
	v_lshlrev_b32_e32 v2, 16, v94
	v_mul_f32_e32 v2, v3, v2
	v_lshlrev_b64 v[0:1], 9, v[0:1]
	v_cvt_pk_bf16_f32 v5, v2, v49
	v_lshl_add_u64 v[2:3], v[74:75], 0, v[0:1]
	global_store_short v[2:3], v5, off
	v_mul_f32_e32 v2, 0xbfb8aa3b, v95
	v_exp_f32_e32 v2, v2
	v_lshlrev_b32_e32 v4, 16, v63
	v_lshl_add_u64 v[0:1], v[76:77], 0, v[0:1]
	v_mul_f32_e32 v2, v2, v4
	v_cvt_pk_bf16_f32 v2, v2, v49
	global_store_short v[0:1], v2, off
.LBB0_302:
	s_or_b64 exec, exec, s[26:27]
	global_load_dwordx4 v[98:101], v[80:81], off offset:16
	global_load_dwordx4 v[102:105], v[80:81], off
	global_load_dwordx4 v[106:109], v[80:81], off offset:48
	global_load_dwordx4 v[110:113], v[80:81], off offset:32
	v_lshlrev_b64 v[0:1], 9, v[78:79]
	v_lshl_add_u64 v[2:3], v[126:127], 0, v[0:1]
	v_lshl_add_u64 v[0:1], v[74:75], 0, v[0:1]
	global_load_ushort v94, v[2:3], off
	global_load_ushort v96, v[0:1], off
	global_load_dwordx4 v[32:35], v[86:87], off offset:48
	global_load_dwordx4 v[36:39], v[86:87], off offset:32
	global_load_dwordx4 v[40:43], v[86:87], off offset:16
	global_load_dwordx4 v[44:47], v[86:87], off
	v_lshlrev_b64 v[0:1], 9, v[82:83]
	v_lshl_add_u64 v[2:3], v[126:127], 0, v[0:1]
	v_lshl_add_u64 v[0:1], v[74:75], 0, v[0:1]
	global_load_ushort v81, v[2:3], off
	global_load_ushort v82, v[0:1], off
	global_load_dwordx4 v[16:19], v[90:91], off offset:48
	global_load_dwordx4 v[20:23], v[90:91], off offset:32
	global_load_dwordx4 v[24:27], v[90:91], off offset:16
	global_load_dwordx4 v[28:31], v[90:91], off
	v_lshlrev_b64 v[0:1], 9, v[84:85]
	v_lshl_add_u64 v[2:3], v[126:127], 0, v[0:1]
	v_lshl_add_u64 v[0:1], v[74:75], 0, v[0:1]
	global_load_ushort v79, v[2:3], off
	global_load_ushort v80, v[0:1], off
	s_nop 0
	global_load_dwordx4 v[0:3], v[92:93], off offset:48
	global_load_dwordx4 v[4:7], v[92:93], off offset:32
	global_load_dwordx4 v[8:11], v[92:93], off offset:16
	global_load_dwordx4 v[12:15], v[92:93], off
	v_lshlrev_b64 v[84:85], 9, v[88:89]
	v_lshl_add_u64 v[86:87], v[126:127], 0, v[84:85]
	v_lshl_add_u64 v[84:85], v[74:75], 0, v[84:85]
	global_load_ushort v63, v[86:87], off
	global_load_ushort v78, v[84:85], off
	s_waitcnt vmcnt(23)
	v_pk_mul_f32 v[84:85], v[66:67], v[100:101]
	s_waitcnt vmcnt(22)
	v_fma_f32 v83, v139, v102, v138
	v_fmac_f32_e32 v83, v140, v103
	v_fmac_f32_e32 v83, v141, v104
	v_fmac_f32_e32 v83, v143, v105
	v_fmac_f32_e32 v83, v142, v98
	v_fmac_f32_e32 v83, v48, v99
	v_add_f32_e32 v83, v83, v84
	v_add_f32_e32 v83, v83, v85
	s_waitcnt vmcnt(20)
	v_pk_mul_f32 v[84:85], v[68:69], v[110:111]
	s_nop 0
	v_add_f32_e32 v83, v83, v84
	v_add_f32_e32 v83, v83, v85
	v_pk_mul_f32 v[84:85], v[64:65], v[112:113]
	s_nop 0
	v_add_f32_e32 v83, v83, v84
	v_add_f32_e32 v83, v83, v85
	v_pk_mul_f32 v[84:85], v[72:73], v[106:107]
	s_nop 0
	v_add_f32_e32 v83, v83, v84
	v_add_f32_e32 v83, v83, v85
	v_pk_mul_f32 v[84:85], v[70:71], v[108:109]
	s_nop 0
	v_add_f32_e32 v83, v83, v84
	v_add_f32_e32 v83, v83, v85
	v_mul_f32_e64 v84, |v83|, s97
	v_exp_f32_e32 v86, v84
	v_min_f32_e32 v83, 0, v83
	s_nop 7
	s_nop 7
	s_nop 3
	v_add_f32_e32 v84, 1.0, v86
	v_log_f32_e32 v84, v84
	s_nop 0
	v_mul_f32_e32 v84, 0x3f317218, v84
	s_nop 1
	v_sub_f32_e32 v83, v83, v84
	v_mul_f32_e32 v83, 0x3d800000, v83
	v_cndmask_b32_e64 v83, 0, v83, s[28:29]
	v_add_f32_e32 v83, v95, v83
	s_and_saveexec_b64 s[22:23], s[28:29]
	s_cbranch_execz .LBB0_304
	v_mul_f32_e32 v87, 0x3fb8aa3b, v83
	v_exp_f32_e32 v87, v87
	v_add_u32_e32 v84, s54, v177
	v_ashrrev_i32_e32 v85, 31, v84
	s_waitcnt vmcnt(18)
	v_lshlrev_b32_e32 v86, 16, v96
	v_mul_f32_e32 v86, v87, v86
	v_lshlrev_b64 v[84:85], 9, v[84:85]
	v_cvt_pk_bf16_f32 v89, v86, v49
	v_lshl_add_u64 v[86:87], v[74:75], 0, v[84:85]
	global_store_short v[86:87], v89, off
	v_mul_f32_e32 v86, 0xbfb8aa3b, v83
	v_exp_f32_e32 v86, v86
	v_lshlrev_b32_e32 v88, 16, v94
	v_lshl_add_u64 v[84:85], v[76:77], 0, v[84:85]
	v_mul_f32_e32 v86, v86, v88
	v_cvt_pk_bf16_f32 v86, v86, v49
	global_store_short v[84:85], v86, off
.LBB0_304:
	s_or_b64 exec, exec, s[22:23]
	s_waitcnt vmcnt(14)
	v_fma_f32 v44, v139, v44, v138
	v_fmac_f32_e32 v44, v140, v45
	v_fmac_f32_e32 v44, v141, v46
	v_fmac_f32_e32 v44, v143, v47
	v_fmac_f32_e32 v44, v142, v40
	v_fmac_f32_e32 v44, v48, v41
	v_pk_mul_f32 v[40:41], v[66:67], v[42:43]
	v_pk_mul_f32 v[36:37], v[68:69], v[36:37]
	v_add_f32_e32 v40, v44, v40
	v_add_f32_e32 v40, v40, v41
	v_add_f32_e32 v36, v40, v36
	v_add_f32_e32 v40, v36, v37
	v_pk_mul_f32 v[36:37], v[64:65], v[38:39]
	v_pk_mul_f32 v[32:33], v[72:73], v[32:33]
	v_add_f32_e32 v36, v40, v36
	v_add_f32_e32 v36, v36, v37
	v_add_f32_e32 v32, v36, v32
	v_add_f32_e32 v36, v32, v33
	v_pk_mul_f32 v[32:33], v[70:71], v[34:35]
	s_nop 0
	v_add_f32_e32 v32, v36, v32
	v_add_f32_e32 v32, v32, v33
	v_mul_f32_e64 v33, |v32|, s97
	v_exp_f32_e32 v34, v33
	v_min_f32_e32 v35, 0, v32
	s_nop 7
	s_nop 7
	s_nop 3
	v_add_f32_e32 v32, 1.0, v34
	v_log_f32_e32 v32, v32
	s_nop 0
	v_mul_f32_e32 v32, 0x3f317218, v32
	s_nop 1
	v_sub_f32_e32 v32, v35, v32
	v_mul_f32_e32 v32, 0x3d800000, v32
	v_cndmask_b32_e64 v32, 0, v32, s[24:25]
	v_add_f32_e32 v32, v83, v32
	s_and_saveexec_b64 s[22:23], s[24:25]
	s_cbranch_execz .LBB0_306
	v_mul_f32_e32 v37, 0x3fb8aa3b, v32
	v_exp_f32_e32 v37, v37
	v_add_u32_e32 v34, s54, v147
	v_ashrrev_i32_e32 v35, 31, v34
	s_waitcnt vmcnt(12)
	v_lshlrev_b32_e32 v36, 16, v82
	v_mul_f32_e32 v36, v37, v36
	v_lshlrev_b64 v[34:35], 9, v[34:35]
	v_cvt_pk_bf16_f32 v38, v36, v49
	v_lshl_add_u64 v[36:37], v[74:75], 0, v[34:35]
	global_store_short v[36:37], v38, off
	v_mul_f32_e32 v36, 0xbfb8aa3b, v32
	v_exp_f32_e32 v36, v36
	v_lshlrev_b32_e32 v33, 16, v81
	v_lshl_add_u64 v[34:35], v[76:77], 0, v[34:35]
	v_mul_f32_e32 v33, v36, v33
	v_cvt_pk_bf16_f32 v33, v33, v49
	global_store_short v[34:35], v33, off
.LBB0_306:
	s_or_b64 exec, exec, s[22:23]
	s_waitcnt vmcnt(8)
	v_fma_f32 v28, v139, v28, v138
	v_fmac_f32_e32 v28, v140, v29
	v_fmac_f32_e32 v28, v141, v30
	v_fmac_f32_e32 v28, v143, v31
	v_fmac_f32_e32 v28, v142, v24
	v_fmac_f32_e32 v28, v48, v25
	v_pk_mul_f32 v[24:25], v[66:67], v[26:27]
	v_pk_mul_f32 v[20:21], v[68:69], v[20:21]
	v_add_f32_e32 v24, v28, v24
	v_add_f32_e32 v24, v24, v25
	v_add_f32_e32 v20, v24, v20
	v_add_f32_e32 v24, v20, v21
	v_pk_mul_f32 v[20:21], v[64:65], v[22:23]
	v_pk_mul_f32 v[16:17], v[72:73], v[16:17]
	v_add_f32_e32 v20, v24, v20
	v_add_f32_e32 v20, v20, v21
	v_add_f32_e32 v16, v20, v16
	v_add_f32_e32 v20, v16, v17
	v_pk_mul_f32 v[16:17], v[70:71], v[18:19]
	s_nop 0
	v_add_f32_e32 v16, v20, v16
	v_add_f32_e32 v16, v16, v17
	v_mul_f32_e64 v17, |v16|, s97
	v_exp_f32_e32 v18, v17
	v_min_f32_e32 v19, 0, v16
	s_nop 7
	s_nop 7
	s_nop 3
	v_add_f32_e32 v16, 1.0, v18
	v_log_f32_e32 v16, v16
	s_nop 0
	v_mul_f32_e32 v16, 0x3f317218, v16
	s_nop 1
	v_sub_f32_e32 v16, v19, v16
	v_mul_f32_e32 v16, 0x3d800000, v16
	v_cndmask_b32_e64 v16, 0, v16, s[20:21]
	v_add_f32_e32 v16, v32, v16
	s_and_saveexec_b64 s[22:23], s[20:21]
	s_cbranch_execz .LBB0_308
	v_mul_f32_e32 v21, 0x3fb8aa3b, v16
	v_exp_f32_e32 v21, v21
	v_add_u32_e32 v18, s54, v145
	v_ashrrev_i32_e32 v19, 31, v18
	s_waitcnt vmcnt(6)
	v_lshlrev_b32_e32 v20, 16, v80
	v_mul_f32_e32 v20, v21, v20
	v_lshlrev_b64 v[18:19], 9, v[18:19]
	v_cvt_pk_bf16_f32 v22, v20, v49
	v_lshl_add_u64 v[20:21], v[74:75], 0, v[18:19]
	global_store_short v[20:21], v22, off
	v_mul_f32_e32 v20, 0xbfb8aa3b, v16
	v_exp_f32_e32 v20, v20
	v_lshlrev_b32_e32 v17, 16, v79
	v_lshl_add_u64 v[18:19], v[76:77], 0, v[18:19]
	v_mul_f32_e32 v17, v20, v17
	v_cvt_pk_bf16_f32 v17, v17, v49
	global_store_short v[18:19], v17, off
.LBB0_308:
	s_or_b64 exec, exec, s[22:23]
	s_and_saveexec_b64 s[20:21], vcc
	s_cbranch_execz .LBB0_310
	s_waitcnt vmcnt(2)
	v_fmac_f32_e32 v138, v139, v12
	v_fmac_f32_e32 v138, v140, v13
	v_fmac_f32_e32 v138, v141, v14
	v_fmac_f32_e32 v138, v143, v15
	v_fmac_f32_e32 v138, v142, v8
	v_fmac_f32_e32 v138, v48, v9
	v_pk_mul_f32 v[8:9], v[66:67], v[10:11]
	v_pk_mul_f32 v[4:5], v[68:69], v[4:5]
	v_add_f32_e32 v8, v138, v8
	v_add_f32_e32 v8, v8, v9
	v_add_f32_e32 v4, v8, v4
	v_add_f32_e32 v8, v4, v5
	v_pk_mul_f32 v[4:5], v[64:65], v[6:7]
	v_pk_mul_f32 v[0:1], v[72:73], v[0:1]
	v_add_f32_e32 v4, v8, v4
	v_add_f32_e32 v4, v4, v5
	v_add_f32_e32 v0, v4, v0
	v_add_f32_e32 v4, v0, v1
	v_pk_mul_f32 v[0:1], v[70:71], v[2:3]
	s_nop 0
	v_add_f32_e32 v0, v4, v0
	v_add_f32_e32 v2, v0, v1
	v_mul_f32_e64 v0, |v2|, s97
	v_exp_f32_e32 v3, v0
	v_min_f32_e32 v2, 0, v2
	s_nop 1
	s_waitcnt vmcnt(1)
	v_lshlrev_b32_e32 v4, 16, v63
	s_nop 7
	s_nop 3
	v_add_f32_e32 v0, 1.0, v3
	v_log_f32_e32 v0, v0
	s_nop 0
	v_mul_f32_e32 v0, 0x3f317218, v0
	s_nop 1
	v_sub_f32_e32 v0, v2, v0
	v_fmac_f32_e32 v16, 0x3d800000, v0
	v_mul_f32_e32 v0, 0x3fb8aa3b, v16
	v_exp_f32_e32 v2, v0
	s_waitcnt vmcnt(0)
	v_lshlrev_b32_e32 v3, 16, v78
	v_add_u32_e32 v0, s54, v144
	v_ashrrev_i32_e32 v1, 31, v0
	v_mul_f32_e32 v2, v2, v3
	v_cvt_pk_bf16_f32 v5, v2, v49
	v_mul_f32_e32 v2, 0xbfb8aa3b, v16
	v_exp_f32_e32 v6, v2
	v_lshlrev_b64 v[0:1], 9, v[0:1]
	v_lshl_add_u64 v[2:3], v[74:75], 0, v[0:1]
	global_store_short v[2:3], v5, off
	v_mul_f32_e32 v2, v6, v4
	v_lshl_add_u64 v[0:1], v[76:77], 0, v[0:1]
	v_cvt_pk_bf16_f32 v2, v2, v49
	global_store_short v[0:1], v2, off

.LBB0_787:
	s_waitcnt lgkmcnt(0)
	ds_read_b128 v[0:3], v16
	v_add_u32_e32 v8, s79, v15
	s_and_saveexec_b64 s[22:23], s[16:17]
	s_xor_b64 s[22:23], exec, s[22:23]
	s_cbranch_execz .LBB0_822
	s_mov_b64 s[60:61], -1
	s_and_b64 vcc, exec, s[24:25]
	s_cbranch_vccz .LBB0_820
	s_and_b64 vcc, exec, s[26:27]
	s_cbranch_vccz .LBB0_817
	s_and_saveexec_b64 s[60:61], s[18:19]
	s_xor_b64 s[60:61], exec, s[60:61]
	s_cbranch_execz .LBB0_798
	s_andn2_b64 vcc, exec, s[28:29]
	s_cbranch_vccnz .LBB0_798
	s_and_saveexec_b64 s[62:63], s[20:21]
	s_xor_b64 s[62:63], exec, s[62:63]
	s_cbranch_execz .LBB0_795
	s_andn2_b64 vcc, exec, s[58:59]
	s_cbranch_vccnz .LBB0_795
	v_ashrrev_i32_e32 v9, 31, v8
	v_lshlrev_b64 v[10:11], 8, v[8:9]
	s_waitcnt lgkmcnt(0)
	v_mul_f32_e32 v9, 0xbfb8aa3b, v0
	v_exp_f32_e32 v9, v9
	v_lshl_add_u64 v[10:11], v[4:5], 0, v[10:11]
	v_add_f32_e32 v9, 1.0, v9
	s_nop 2
	v_rcp_f32_e32 v9, v9
	s_nop 2
	v_mul_f32_e32 v20, 0xbfb8aa3b, v1
	v_exp_f32_e32 v20, v20
	s_nop 0
	v_add_f32_e32 v20, 1.0, v20
	s_nop 2
	v_rcp_f32_e32 v20, v20
	s_nop 2
	v_mul_f32_e32 v21, 0xbfb8aa3b, v2
	v_exp_f32_e32 v21, v21
	v_cvt_pk_bf16_f32 v20, v9, v20
	s_nop 0
	v_add_f32_e32 v21, 1.0, v21
	s_nop 2
	v_rcp_f32_e32 v21, v21
	s_nop 2
	v_mul_f32_e32 v22, 0xbfb8aa3b, v3
	v_exp_f32_e32 v22, v22
	s_nop 0
	v_add_f32_e32 v22, 1.0, v22
	s_nop 4
	v_add_co_u32_e32 v10, vcc, 0x3971e000, v10
	v_rcp_f32_e32 v22, v22
	s_nop 3
	v_addc_co_u32_e32 v11, vcc, 0, v11, vcc
	v_cvt_pk_bf16_f32 v21, v21, v22
	global_store_dwordx2 v[10:11], v[20:21], off offset:1536

.LBB0_824:
	s_or_b64 exec, exec, s[22:23]
	s_waitcnt lgkmcnt(0)
	ds_read_b128 v[0:3], v17
	v_cndmask_b32_e64 v9, 0, 1, s[24:25]
	v_add_u32_e32 v8, s79, v14
	v_cmp_ne_u32_e64 s[22:23], 1, v9
	s_and_saveexec_b64 s[60:61], s[16:17]
	s_xor_b64 s[60:61], exec, s[60:61]
	s_cbranch_execz .LBB0_859
	s_and_b64 vcc, exec, s[22:23]
	s_mov_b64 s[62:63], -1
	s_cbranch_vccnz .LBB0_857
	s_andn2_b64 vcc, exec, s[26:27]
	s_cbranch_vccnz .LBB0_854
	s_and_saveexec_b64 s[62:63], s[18:19]
	s_xor_b64 s[62:63], exec, s[62:63]
	s_cbranch_execz .LBB0_835
	s_andn2_b64 vcc, exec, s[28:29]
	s_cbranch_vccnz .LBB0_835
	s_and_saveexec_b64 s[64:65], s[20:21]
	s_xor_b64 s[64:65], exec, s[64:65]
	s_cbranch_execz .LBB0_832
	s_andn2_b64 vcc, exec, s[58:59]
	s_cbranch_vccnz .LBB0_832
	v_ashrrev_i32_e32 v9, 31, v8
	v_lshlrev_b64 v[10:11], 8, v[8:9]
	s_waitcnt lgkmcnt(0)
	v_mul_f32_e32 v9, 0xbfb8aa3b, v0
	v_exp_f32_e32 v9, v9
	v_lshl_add_u64 v[10:11], v[4:5], 0, v[10:11]
	v_add_f32_e32 v9, 1.0, v9
	s_nop 2
	v_rcp_f32_e32 v9, v9
	s_nop 2
	v_mul_f32_e32 v20, 0xbfb8aa3b, v1
	v_exp_f32_e32 v20, v20
	s_nop 0
	v_add_f32_e32 v20, 1.0, v20
	s_nop 2
	v_rcp_f32_e32 v20, v20
	s_nop 2
	v_mul_f32_e32 v21, 0xbfb8aa3b, v2
	v_exp_f32_e32 v21, v21
	v_cvt_pk_bf16_f32 v20, v9, v20
	s_nop 0
	v_add_f32_e32 v21, 1.0, v21
	s_nop 2
	v_rcp_f32_e32 v21, v21
	s_nop 2
	v_mul_f32_e32 v22, 0xbfb8aa3b, v3
	v_exp_f32_e32 v22, v22
	s_nop 0
	v_add_f32_e32 v22, 1.0, v22
	s_nop 4
	v_add_co_u32_e32 v10, vcc, 0x3971e000, v10
	v_rcp_f32_e32 v22, v22
	s_nop 3
	v_addc_co_u32_e32 v11, vcc, 0, v11, vcc
	v_cvt_pk_bf16_f32 v21, v21, v22
	global_store_dwordx2 v[10:11], v[20:21], off offset:1536

.LBB0_861:
	s_or_b64 exec, exec, s[60:61]
	s_waitcnt lgkmcnt(0)
	ds_read_b128 v[0:3], v18
	v_add_u32_e32 v8, s79, v13
	s_and_saveexec_b64 s[60:61], s[16:17]
	s_xor_b64 s[60:61], exec, s[60:61]
	s_cbranch_execz .LBB0_896
	s_and_b64 vcc, exec, s[22:23]
	s_mov_b64 s[62:63], -1
	s_cbranch_vccnz .LBB0_894
	s_andn2_b64 vcc, exec, s[26:27]
	s_cbranch_vccnz .LBB0_891
	s_and_saveexec_b64 s[62:63], s[18:19]
	s_xor_b64 s[62:63], exec, s[62:63]
	s_cbranch_execz .LBB0_872
	s_andn2_b64 vcc, exec, s[28:29]
	s_cbranch_vccnz .LBB0_872
	s_and_saveexec_b64 s[64:65], s[20:21]
	s_xor_b64 s[64:65], exec, s[64:65]
	s_cbranch_execz .LBB0_869
	s_andn2_b64 vcc, exec, s[58:59]
	s_cbranch_vccnz .LBB0_869
	v_ashrrev_i32_e32 v9, 31, v8
	v_lshlrev_b64 v[10:11], 8, v[8:9]
	s_waitcnt lgkmcnt(0)
	v_mul_f32_e32 v9, 0xbfb8aa3b, v0
	v_exp_f32_e32 v9, v9
	v_lshl_add_u64 v[10:11], v[4:5], 0, v[10:11]
	v_add_f32_e32 v9, 1.0, v9
	s_nop 2
	v_rcp_f32_e32 v9, v9
	s_nop 2
	v_mul_f32_e32 v20, 0xbfb8aa3b, v1
	v_exp_f32_e32 v20, v20
	s_nop 0
	v_add_f32_e32 v20, 1.0, v20
	s_nop 2
	v_rcp_f32_e32 v20, v20
	s_nop 2
	v_mul_f32_e32 v21, 0xbfb8aa3b, v2
	v_exp_f32_e32 v21, v21
	v_cvt_pk_bf16_f32 v20, v9, v20
	s_nop 0
	v_add_f32_e32 v21, 1.0, v21
	s_nop 2
	v_rcp_f32_e32 v21, v21
	s_nop 2
	v_mul_f32_e32 v22, 0xbfb8aa3b, v3
	v_exp_f32_e32 v22, v22
	s_nop 0
	v_add_f32_e32 v22, 1.0, v22
	s_nop 4
	v_add_co_u32_e32 v10, vcc, 0x3971e000, v10
	v_rcp_f32_e32 v22, v22
	s_nop 3
	v_addc_co_u32_e32 v11, vcc, 0, v11, vcc
	v_cvt_pk_bf16_f32 v21, v21, v22
	global_store_dwordx2 v[10:11], v[20:21], off offset:1536

.LBB0_898:
	s_or_b64 exec, exec, s[60:61]
	s_waitcnt lgkmcnt(0)
	ds_read_b128 v[0:3], v19
	v_add_u32_e32 v8, s79, v12
	s_and_saveexec_b64 s[60:61], s[16:17]
	s_xor_b64 s[60:61], exec, s[60:61]
	s_cbranch_execz .LBB0_933
	s_and_b64 vcc, exec, s[22:23]
	s_mov_b64 s[22:23], -1
	s_cbranch_vccnz .LBB0_931
	s_andn2_b64 vcc, exec, s[26:27]
	s_cbranch_vccnz .LBB0_928
	s_and_saveexec_b64 s[22:23], s[18:19]
	s_xor_b64 s[22:23], exec, s[22:23]
	s_cbranch_execz .LBB0_909
	s_andn2_b64 vcc, exec, s[28:29]
	s_cbranch_vccnz .LBB0_909
	s_and_saveexec_b64 s[62:63], s[20:21]
	s_xor_b64 s[62:63], exec, s[62:63]
	s_cbranch_execz .LBB0_906
	s_andn2_b64 vcc, exec, s[58:59]
	s_cbranch_vccnz .LBB0_906
	v_ashrrev_i32_e32 v9, 31, v8
	v_lshlrev_b64 v[10:11], 8, v[8:9]
	s_waitcnt lgkmcnt(0)
	v_mul_f32_e32 v9, 0xbfb8aa3b, v0
	v_exp_f32_e32 v9, v9
	v_lshl_add_u64 v[10:11], v[4:5], 0, v[10:11]
	v_add_f32_e32 v9, 1.0, v9
	s_nop 2
	v_rcp_f32_e32 v9, v9
	s_nop 2
	v_mul_f32_e32 v20, 0xbfb8aa3b, v1
	v_exp_f32_e32 v20, v20
	s_nop 0
	v_add_f32_e32 v20, 1.0, v20
	s_nop 2
	v_rcp_f32_e32 v20, v20
	s_nop 2
	v_mul_f32_e32 v21, 0xbfb8aa3b, v2
	v_exp_f32_e32 v21, v21
	v_cvt_pk_bf16_f32 v20, v9, v20
	s_nop 0
	v_add_f32_e32 v21, 1.0, v21
	s_nop 2
	v_rcp_f32_e32 v21, v21
	s_nop 2
	v_mul_f32_e32 v22, 0xbfb8aa3b, v3
	v_exp_f32_e32 v22, v22
	s_nop 0
	v_add_f32_e32 v22, 1.0, v22
	s_nop 4
	v_add_co_u32_e32 v10, vcc, 0x3971e000, v10
	v_rcp_f32_e32 v22, v22
	s_nop 3
	v_addc_co_u32_e32 v11, vcc, 0, v11, vcc
	v_cvt_pk_bf16_f32 v21, v21, v22
	global_store_dwordx2 v[10:11], v[20:21], off offset:1536

.LBB0_952:
	s_nop 0
	ds_read_b128 v[0:3], v20
	v_lshl_add_u64 v[18:19], v[16:17], 0, s[8:9]
	v_add_u32_e32 v20, 0x4200, v20
	s_waitcnt lgkmcnt(0)
	v_add_f32_e32 v0, v0, v28
	v_mul_f32_e32 v0, 0xbfb8aa3b, v0
	v_exp_f32_e32 v0, v0
	v_add_f32_e32 v1, v1, v29
	v_mul_f32_e32 v1, 0xbfb8aa3b, v1
	v_exp_f32_e32 v1, v1
	v_add_f32_e32 v0, 1.0, v0
	s_nop 1
	v_add_f32_e32 v1, 1.0, v1
	v_add_f32_e32 v2, v2, v30
	v_mul_f32_e32 v2, 0xbfb8aa3b, v2
	v_rcp_f32_e32 v0, v0
	s_nop 2
	v_exp_f32_e32 v2, v2
	v_add_f32_e32 v3, v3, v31
	v_mul_f32_e32 v3, 0xbfb8aa3b, v3
	s_nop 1
	v_add_f32_e32 v2, 1.0, v2
	v_rcp_f32_e32 v1, v1
	s_nop 2
	v_exp_f32_e32 v3, v3
	v_cvt_pk_bf16_f32 v0, v0, v1
	s_nop 1
	v_add_f32_e32 v3, 1.0, v3
	v_rcp_f32_e32 v2, v2
	s_nop 3
	v_rcp_f32_e32 v3, v3
	s_nop 2
	v_cvt_pk_bf16_f32 v1, v2, v3
	global_store_dwordx2 v[18:19], v[0:1], off
	s_nop 0
	ds_read_b128 v[0:3], v21
	v_lshl_add_u64 v[18:19], v[14:15], 0, s[8:9]
	v_add_u32_e32 v21, 0x4200, v21
	s_waitcnt lgkmcnt(0)
	v_add_f32_e32 v0, v0, v28
	v_mul_f32_e32 v0, 0xbfb8aa3b, v0
	v_exp_f32_e32 v0, v0
	v_add_f32_e32 v1, v1, v29
	v_mul_f32_e32 v1, 0xbfb8aa3b, v1
	v_exp_f32_e32 v1, v1
	v_add_f32_e32 v0, 1.0, v0
	s_nop 1
	v_add_f32_e32 v1, 1.0, v1
	v_add_f32_e32 v2, v2, v30
	v_mul_f32_e32 v2, 0xbfb8aa3b, v2
	v_rcp_f32_e32 v0, v0
	s_nop 2
	v_exp_f32_e32 v2, v2
	v_add_f32_e32 v3, v3, v31
	v_mul_f32_e32 v3, 0xbfb8aa3b, v3
	s_nop 1
	v_add_f32_e32 v2, 1.0, v2
	v_rcp_f32_e32 v1, v1
	s_nop 2
	v_exp_f32_e32 v3, v3
	v_cvt_pk_bf16_f32 v0, v0, v1
	s_nop 1
	v_add_f32_e32 v3, 1.0, v3
	v_rcp_f32_e32 v2, v2
	s_nop 3
	v_rcp_f32_e32 v3, v3
	s_nop 2
	v_cvt_pk_bf16_f32 v1, v2, v3
	global_store_dwordx2 v[18:19], v[0:1], off
	s_nop 0
	ds_read_b128 v[0:3], v22
	v_lshl_add_u64 v[18:19], v[12:13], 0, s[8:9]
	v_add_u32_e32 v22, 0x4200, v22
	s_waitcnt lgkmcnt(0)
	v_add_f32_e32 v0, v0, v28
	v_mul_f32_e32 v0, 0xbfb8aa3b, v0
	v_exp_f32_e32 v0, v0
	v_add_f32_e32 v1, v1, v29
	v_mul_f32_e32 v1, 0xbfb8aa3b, v1
	v_exp_f32_e32 v1, v1
	v_add_f32_e32 v0, 1.0, v0
	s_nop 1
	v_add_f32_e32 v1, 1.0, v1
	v_add_f32_e32 v2, v2, v30
	v_mul_f32_e32 v2, 0xbfb8aa3b, v2
	v_rcp_f32_e32 v0, v0
	s_nop 2
	v_exp_f32_e32 v2, v2
	v_add_f32_e32 v3, v3, v31
	v_mul_f32_e32 v3, 0xbfb8aa3b, v3
	s_nop 1
	v_add_f32_e32 v2, 1.0, v2
	v_rcp_f32_e32 v1, v1
	s_nop 2
	v_exp_f32_e32 v3, v3
	v_cvt_pk_bf16_f32 v0, v0, v1
	s_nop 1
	v_add_f32_e32 v3, 1.0, v3
	v_rcp_f32_e32 v2, v2
	s_nop 3
	v_rcp_f32_e32 v3, v3
	s_nop 2
	v_cvt_pk_bf16_f32 v1, v2, v3
	global_store_dwordx2 v[18:19], v[0:1], off
	s_nop 0
	ds_read_b128 v[0:3], v23
	v_lshl_add_u64 v[18:19], v[10:11], 0, s[8:9]
	s_add_u32 s8, s8, 0x10000
	s_addc_u32 s9, s9, 0
	v_add_u32_e32 v23, 0x4200, v23
	s_cmp_eq_u32 s8, 0x40000
	s_waitcnt lgkmcnt(0)
	v_add_f32_e32 v0, v0, v28
	v_mul_f32_e32 v0, 0xbfb8aa3b, v0
	v_exp_f32_e32 v0, v0
	v_add_f32_e32 v1, v1, v29
	v_mul_f32_e32 v1, 0xbfb8aa3b, v1
	v_exp_f32_e32 v1, v1
	v_add_f32_e32 v0, 1.0, v0
	s_nop 1
	v_add_f32_e32 v1, 1.0, v1
	v_add_f32_e32 v2, v2, v30
	v_mul_f32_e32 v2, 0xbfb8aa3b, v2
	v_rcp_f32_e32 v0, v0
	s_nop 2
	v_exp_f32_e32 v2, v2
	v_add_f32_e32 v3, v3, v31
	v_mul_f32_e32 v3, 0xbfb8aa3b, v3
	s_nop 1
	v_add_f32_e32 v2, 1.0, v2
	v_rcp_f32_e32 v1, v1
	s_nop 2
	v_exp_f32_e32 v3, v3
	v_cvt_pk_bf16_f32 v0, v0, v1
	s_nop 1
	v_add_f32_e32 v3, 1.0, v3
	v_rcp_f32_e32 v2, v2
	s_nop 3
	v_rcp_f32_e32 v3, v3
	s_nop 2
	v_cvt_pk_bf16_f32 v1, v2, v3
	global_store_dwordx2 v[18:19], v[0:1], off
	s_cbranch_scc0 .LBB0_952
